# fused-LN apply: LDS row statistics double-buffered (next row's mean/rstd prefetched during current row)
# baseline (speedup 1.0000x reference)
; template <unsigned D> __device__ __forceinline__ u32x4 rd8(u32x4 w) { w.x = rd<D>(w.x); w.y = rd<D>(w.y); w.z = rd<D>(w.z); w.w = rd<D>(w.w); return w; }
; __device__ __forceinline__ u32x4 pk8(const f32x4 v0, const f32x4 v1) { u32x4 w; w.x = pk_f16(v0[0], v0[1]); w.y = pk_f16(v0[2], v0[3]); w.z = pk_f16(v1[0], v1[1]); w.w = pk_f16(v1[2], v1[3]); return w; }
; __device__ __forceinline__ unsigned pk4_fp8(float a, float b, float c, float d) { int w = __builtin_amdgcn_cvt_pk_fp8_f32(a, b, 0, false); w = __builtin_amdgcn_cvt_pk_fp8_f32(c, d, w, true); return (unsigned)w; }
;     __device__ __forceinline__ void fused(f32x4 (&acc)[2][2][4][2], const GUnit& u, int wr, int wc, int fr, int fq, LAS unsigned char* lds, int wid, int lane) const {
;     ...
; #pragma unroll
;         for (int ai = 0; ai < 2; ++ai)
; #pragma unroll
;             for (int m = 0; m < 4; ++m) { const int r = ai * 128 + wr * 64 + m * 16 + fr; const f32x2 sr = S[r]; const size_t row = (size_t)(u.pm * 256 + r);
; #pragma unroll
;                 for (int bj = 0; bj < 2; ++bj) { const int col = gcol0 + bj * 128;
;                     f32x4 y0 = (acc[ai][bj][m][0] - sr.x) * sr.y * gv[bj][0] + bv[bj][0], y1 = (acc[ai][bj][m][1] - sr.x) * sr.y * gv[bj][1] + bv[bj][1];
;                     if (bad) { y0 = (f32x4){qnan, qnan, qnan, qnan}; y1 = y0; }
;                     if (last) { *(f32x4*)(out + row * 1024 + col) = y0; *(f32x4*)(out + row * 1024 + col + 4) = y1; }
;                     else { *(u32x4*)(H16 + row * 1024 + col) = rd8<D_H>(pk8(y0, y1));
;                            if (h8out) { u32x2 q8v; q8v.x = pk4_fp8(y0[0], y0[1], y0[2], y0[3]); q8v.y = pk4_fp8(y1[0], y1[1], y1[2], y1[3]); *(u32x2*)(ws + WS_H8 + row * 1024 + col) = q8v; } } }
.Lap_mine:
	v_lshl_add_u32 v32, v233, 3, 0
	v_readlane_b32 s2, v253, 4
	v_readlane_b32 s3, v253, 5
	v_cmp_eq_u32_e64 s[100:101], 0, v170
	v_readlane_b32 s6, v252, 26
	v_readlane_b32 s7, v252, 27
	v_lshl_add_u64 v[166:167], s[2:3], 0, v[216:217]
	v_lshl_add_u64 v[166:167], v[198:199], 1, v[166:167]
	v_lshlrev_b64 v[178:179], 10, v[214:215]
	v_lshl_add_u64 v[178:179], s[6:7], 0, v[178:179]
	v_lshl_add_u64 v[178:179], v[178:179], 0, v[198:199]
	s_and_b64 vcc, exec, s[16:17]
	s_cbranch_vccnz .Lap_d
	ds_read_b64 v[168:169], v32 offset:8192
	ds_read_b64 v[164:165], v32 offset:8320
	s_waitcnt vmcnt(0) lgkmcnt(1)
	v_cndmask_b32_e64 v169, v229, v169, s[100:101]
	v_pk_add_f32 v[128:129], v[128:129], v[168:169] op_sel_hi:[1,0] neg_lo:[0,1] neg_hi:[0,1]
	v_pk_add_f32 v[130:131], v[130:131], v[168:169] op_sel_hi:[1,0] neg_lo:[0,1] neg_hi:[0,1]
	v_pk_add_f32 v[124:125], v[124:125], v[168:169] op_sel_hi:[1,0] neg_lo:[0,1] neg_hi:[0,1]
	v_pk_add_f32 v[126:127], v[126:127], v[168:169] op_sel_hi:[1,0] neg_lo:[0,1] neg_hi:[0,1]
	v_pk_mul_f32 v[128:129], v[168:169], v[128:129] op_sel:[1,0]
	v_pk_mul_f32 v[130:131], v[168:169], v[130:131] op_sel:[1,0]
	v_pk_mul_f32 v[124:125], v[168:169], v[124:125] op_sel:[1,0]
	v_pk_mul_f32 v[126:127], v[168:169], v[126:127] op_sel:[1,0]
	v_pk_fma_f32 v[128:129], v[160:161], v[128:129], v[156:157]
	v_pk_fma_f32 v[130:131], v[162:163], v[130:131], v[158:159]
	v_pk_fma_f32 v[124:125], v[148:149], v[124:125], v[152:153]
	v_pk_fma_f32 v[126:127], v[150:151], v[126:127], v[154:155]
	v_cvt_pk_f16_f32 v170, v128, v129
	v_cvt_pk_f16_f32 v171, v130, v131
	v_cvt_pk_f16_f32 v172, v124, v125
	v_cvt_pk_f16_f32 v173, v126, v127
	v_add_u32_e32 v170, 0x20002, v170
	v_add_u32_e32 v171, 0x20002, v171
	v_add_u32_e32 v172, 0x20002, v172
	v_add_u32_e32 v173, 0x20002, v173
	v_and_b32_e32 v170, 0xfffcfffc, v170
	v_and_b32_e32 v171, 0xfffcfffc, v171
	v_and_b32_e32 v172, 0xfffcfffc, v172
	v_and_b32_e32 v173, 0xfffcfffc, v173
	global_store_dwordx4 v[166:167], v[170:173], off
	v_cvt_pk_fp8_f32 v174, v128, v129
	v_cvt_pk_fp8_f32 v175, v124, v125
	v_cvt_pk_fp8_f32 v174, v130, v131 op_sel:[0,0,1]
	v_cvt_pk_fp8_f32 v175, v126, v127 op_sel:[0,0,1]
	global_store_dwordx2 v[178:179], v[174:175], off
	v_pk_add_f32 v[120:121], v[120:121], v[168:169] op_sel_hi:[1,0] neg_lo:[0,1] neg_hi:[0,1]
	v_pk_add_f32 v[122:123], v[122:123], v[168:169] op_sel_hi:[1,0] neg_lo:[0,1] neg_hi:[0,1]
	v_pk_add_f32 v[116:117], v[116:117], v[168:169] op_sel_hi:[1,0] neg_lo:[0,1] neg_hi:[0,1]
	v_pk_add_f32 v[118:119], v[118:119], v[168:169] op_sel_hi:[1,0] neg_lo:[0,1] neg_hi:[0,1]
	v_pk_mul_f32 v[120:121], v[168:169], v[120:121] op_sel:[1,0]
	v_pk_mul_f32 v[122:123], v[168:169], v[122:123] op_sel:[1,0]
	v_pk_mul_f32 v[116:117], v[168:169], v[116:117] op_sel:[1,0]
	v_pk_mul_f32 v[118:119], v[168:169], v[118:119] op_sel:[1,0]
	v_pk_fma_f32 v[120:121], v[140:141], v[120:121], v[144:145]
	v_pk_fma_f32 v[122:123], v[142:143], v[122:123], v[146:147]
	v_pk_fma_f32 v[116:117], v[132:133], v[116:117], v[136:137]
	v_pk_fma_f32 v[118:119], v[134:135], v[118:119], v[138:139]
	v_cvt_pk_f16_f32 v170, v120, v121
	v_cvt_pk_f16_f32 v171, v122, v123
	v_cvt_pk_f16_f32 v172, v116, v117
	v_cvt_pk_f16_f32 v173, v118, v119
	v_add_u32_e32 v170, 0x20002, v170
	v_add_u32_e32 v171, 0x20002, v171
	v_add_u32_e32 v172, 0x20002, v172
	v_add_u32_e32 v173, 0x20002, v173
	v_and_b32_e32 v170, 0xfffcfffc, v170
	v_and_b32_e32 v171, 0xfffcfffc, v171
	v_and_b32_e32 v172, 0xfffcfffc, v172
	v_and_b32_e32 v173, 0xfffcfffc, v173
	global_store_dwordx4 v[166:167], v[170:173], off offset:256
	v_cvt_pk_fp8_f32 v174, v120, v121
	v_cvt_pk_fp8_f32 v175, v116, v117
	v_cvt_pk_fp8_f32 v174, v122, v123 op_sel:[0,0,1]
	v_cvt_pk_fp8_f32 v175, v118, v119 op_sel:[0,0,1]
	global_store_dwordx2 v[178:179], v[174:175], off offset:128
	ds_read_b64 v[168:169], v32 offset:8448
	v_add_co_u32_e32 v176, vcc, 0x8000, v166
	v_addc_co_u32_e32 v177, vcc, 0, v167, vcc
	v_add_co_u32_e32 v180, vcc, 0x4000, v178
	v_addc_co_u32_e32 v181, vcc, 0, v179, vcc
	s_waitcnt lgkmcnt(1)
	v_cndmask_b32_e64 v165, v229, v165, s[100:101]
	v_pk_add_f32 v[112:113], v[112:113], v[164:165] op_sel_hi:[1,0] neg_lo:[0,1] neg_hi:[0,1]
	v_pk_add_f32 v[114:115], v[114:115], v[164:165] op_sel_hi:[1,0] neg_lo:[0,1] neg_hi:[0,1]
	v_pk_add_f32 v[108:109], v[108:109], v[164:165] op_sel_hi:[1,0] neg_lo:[0,1] neg_hi:[0,1]
	v_pk_add_f32 v[110:111], v[110:111], v[164:165] op_sel_hi:[1,0] neg_lo:[0,1] neg_hi:[0,1]
	v_pk_mul_f32 v[112:113], v[164:165], v[112:113] op_sel:[1,0]
	v_pk_mul_f32 v[114:115], v[164:165], v[114:115] op_sel:[1,0]
	v_pk_mul_f32 v[108:109], v[164:165], v[108:109] op_sel:[1,0]
	v_pk_mul_f32 v[110:111], v[164:165], v[110:111] op_sel:[1,0]
	v_pk_fma_f32 v[112:113], v[160:161], v[112:113], v[156:157]
	v_pk_fma_f32 v[114:115], v[162:163], v[114:115], v[158:159]
	v_pk_fma_f32 v[108:109], v[148:149], v[108:109], v[152:153]
	v_pk_fma_f32 v[110:111], v[150:151], v[110:111], v[154:155]
	v_cvt_pk_f16_f32 v170, v112, v113
	v_cvt_pk_f16_f32 v171, v114, v115
	v_cvt_pk_f16_f32 v172, v108, v109
	v_cvt_pk_f16_f32 v173, v110, v111
	v_add_u32_e32 v170, 0x20002, v170
	v_add_u32_e32 v171, 0x20002, v171
	v_add_u32_e32 v172, 0x20002, v172
	v_add_u32_e32 v173, 0x20002, v173
	v_and_b32_e32 v170, 0xfffcfffc, v170
	v_and_b32_e32 v171, 0xfffcfffc, v171
	v_and_b32_e32 v172, 0xfffcfffc, v172
	v_and_b32_e32 v173, 0xfffcfffc, v173
	global_store_dwordx4 v[176:177], v[170:173], off
	v_cvt_pk_fp8_f32 v174, v112, v113
	v_cvt_pk_fp8_f32 v175, v108, v109
	v_cvt_pk_fp8_f32 v174, v114, v115 op_sel:[0,0,1]
	v_cvt_pk_fp8_f32 v175, v110, v111 op_sel:[0,0,1]
	global_store_dwordx2 v[180:181], v[174:175], off
; template <unsigned D> __device__ __forceinline__ u32x4 rd8(u32x4 w) { w.x = rd<D>(w.x); w.y = rd<D>(w.y); w.z = rd<D>(w.z); w.w = rd<D>(w.w); return w; }
; __device__ __forceinline__ u32x4 pk8(const f32x4 v0, const f32x4 v1) { u32x4 w; w.x = pk_f16(v0[0], v0[1]); w.y = pk_f16(v0[2], v0[3]); w.z = pk_f16(v1[0], v1[1]); w.w = pk_f16(v1[2], v1[3]); return w; }
; __device__ __forceinline__ unsigned pk4_fp8(float a, float b, float c, float d) { int w = __builtin_amdgcn_cvt_pk_fp8_f32(a, b, 0, false); w = __builtin_amdgcn_cvt_pk_fp8_f32(c, d, w, true); return (unsigned)w; }
;     __device__ __forceinline__ void fused(f32x4 (&acc)[2][2][4][2], const GUnit& u, int wr, int wc, int fr, int fq, LAS unsigned char* lds, int wid, int lane) const {
;     ...
; #pragma unroll
;         for (int ai = 0; ai < 2; ++ai)
; #pragma unroll
;             for (int m = 0; m < 4; ++m) { const int r = ai * 128 + wr * 64 + m * 16 + fr; const f32x2 sr = S[r]; const size_t row = (size_t)(u.pm * 256 + r);
; #pragma unroll
;                 for (int bj = 0; bj < 2; ++bj) { const int col = gcol0 + bj * 128;
;                     f32x4 y0 = (acc[ai][bj][m][0] - sr.x) * sr.y * gv[bj][0] + bv[bj][0], y1 = (acc[ai][bj][m][1] - sr.x) * sr.y * gv[bj][1] + bv[bj][1];
;                     if (bad) { y0 = (f32x4){qnan, qnan, qnan, qnan}; y1 = y0; }
;                     if (last) { *(f32x4*)(out + row * 1024 + col) = y0; *(f32x4*)(out + row * 1024 + col + 4) = y1; }
;                     else { *(u32x4*)(H16 + row * 1024 + col) = rd8<D_H>(pk8(y0, y1));
;                            if (h8out) { u32x2 q8v; q8v.x = pk4_fp8(y0[0], y0[1], y0[2], y0[3]); q8v.y = pk4_fp8(y1[0], y1[1], y1[2], y1[3]); *(u32x2*)(ws + WS_H8 + row * 1024 + col) = q8v; } } }
	v_pk_add_f32 v[104:105], v[104:105], v[164:165] op_sel_hi:[1,0] neg_lo:[0,1] neg_hi:[0,1]
	v_pk_add_f32 v[106:107], v[106:107], v[164:165] op_sel_hi:[1,0] neg_lo:[0,1] neg_hi:[0,1]
	v_pk_add_f32 v[100:101], v[100:101], v[164:165] op_sel_hi:[1,0] neg_lo:[0,1] neg_hi:[0,1]
	v_pk_add_f32 v[102:103], v[102:103], v[164:165] op_sel_hi:[1,0] neg_lo:[0,1] neg_hi:[0,1]
	v_pk_mul_f32 v[104:105], v[164:165], v[104:105] op_sel:[1,0]
	v_pk_mul_f32 v[106:107], v[164:165], v[106:107] op_sel:[1,0]
	v_pk_mul_f32 v[100:101], v[164:165], v[100:101] op_sel:[1,0]
	v_pk_mul_f32 v[102:103], v[164:165], v[102:103] op_sel:[1,0]
	v_pk_fma_f32 v[104:105], v[140:141], v[104:105], v[144:145]
	v_pk_fma_f32 v[106:107], v[142:143], v[106:107], v[146:147]
	v_pk_fma_f32 v[100:101], v[132:133], v[100:101], v[136:137]
	v_pk_fma_f32 v[102:103], v[134:135], v[102:103], v[138:139]
	v_cvt_pk_f16_f32 v170, v104, v105
	v_cvt_pk_f16_f32 v171, v106, v107
	v_cvt_pk_f16_f32 v172, v100, v101
	v_cvt_pk_f16_f32 v173, v102, v103
	v_add_u32_e32 v170, 0x20002, v170
	v_add_u32_e32 v171, 0x20002, v171
	v_add_u32_e32 v172, 0x20002, v172
	v_add_u32_e32 v173, 0x20002, v173
	v_and_b32_e32 v170, 0xfffcfffc, v170
	v_and_b32_e32 v171, 0xfffcfffc, v171
	v_and_b32_e32 v172, 0xfffcfffc, v172
	v_and_b32_e32 v173, 0xfffcfffc, v173
	global_store_dwordx4 v[176:177], v[170:173], off offset:256
	v_cvt_pk_fp8_f32 v174, v104, v105
	v_cvt_pk_fp8_f32 v175, v100, v101
	v_cvt_pk_fp8_f32 v174, v106, v107 op_sel:[0,0,1]
	v_cvt_pk_fp8_f32 v175, v102, v103 op_sel:[0,0,1]
	global_store_dwordx2 v[180:181], v[174:175], off offset:128
	ds_read_b64 v[164:165], v32 offset:8576
	v_add_co_u32_e32 v176, vcc, 0x10000, v166
	v_addc_co_u32_e32 v177, vcc, 0, v167, vcc
	v_add_co_u32_e32 v180, vcc, 0x8000, v178
	v_addc_co_u32_e32 v181, vcc, 0, v179, vcc
	s_waitcnt lgkmcnt(1)
	v_cndmask_b32_e64 v169, v229, v169, s[100:101]
	v_pk_add_f32 v[96:97], v[96:97], v[168:169] op_sel_hi:[1,0] neg_lo:[0,1] neg_hi:[0,1]
	v_pk_add_f32 v[98:99], v[98:99], v[168:169] op_sel_hi:[1,0] neg_lo:[0,1] neg_hi:[0,1]
	v_pk_add_f32 v[92:93], v[92:93], v[168:169] op_sel_hi:[1,0] neg_lo:[0,1] neg_hi:[0,1]
	v_pk_add_f32 v[94:95], v[94:95], v[168:169] op_sel_hi:[1,0] neg_lo:[0,1] neg_hi:[0,1]
	v_pk_mul_f32 v[96:97], v[168:169], v[96:97] op_sel:[1,0]
	v_pk_mul_f32 v[98:99], v[168:169], v[98:99] op_sel:[1,0]
	v_pk_mul_f32 v[92:93], v[168:169], v[92:93] op_sel:[1,0]
	v_pk_mul_f32 v[94:95], v[168:169], v[94:95] op_sel:[1,0]
	v_pk_fma_f32 v[96:97], v[160:161], v[96:97], v[156:157]
	v_pk_fma_f32 v[98:99], v[162:163], v[98:99], v[158:159]
	v_pk_fma_f32 v[92:93], v[148:149], v[92:93], v[152:153]
	v_pk_fma_f32 v[94:95], v[150:151], v[94:95], v[154:155]
	v_cvt_pk_f16_f32 v170, v96, v97
	v_cvt_pk_f16_f32 v171, v98, v99
	v_cvt_pk_f16_f32 v172, v92, v93
	v_cvt_pk_f16_f32 v173, v94, v95
	v_add_u32_e32 v170, 0x20002, v170
	v_add_u32_e32 v171, 0x20002, v171
	v_add_u32_e32 v172, 0x20002, v172
	v_add_u32_e32 v173, 0x20002, v173
	v_and_b32_e32 v170, 0xfffcfffc, v170
	v_and_b32_e32 v171, 0xfffcfffc, v171
	v_and_b32_e32 v172, 0xfffcfffc, v172
	v_and_b32_e32 v173, 0xfffcfffc, v173
	global_store_dwordx4 v[176:177], v[170:173], off
	v_cvt_pk_fp8_f32 v174, v96, v97
	v_cvt_pk_fp8_f32 v175, v92, v93
	v_cvt_pk_fp8_f32 v174, v98, v99 op_sel:[0,0,1]
	v_cvt_pk_fp8_f32 v175, v94, v95 op_sel:[0,0,1]
	global_store_dwordx2 v[180:181], v[174:175], off
	v_pk_add_f32 v[88:89], v[88:89], v[168:169] op_sel_hi:[1,0] neg_lo:[0,1] neg_hi:[0,1]
	v_pk_add_f32 v[90:91], v[90:91], v[168:169] op_sel_hi:[1,0] neg_lo:[0,1] neg_hi:[0,1]
	v_pk_add_f32 v[84:85], v[84:85], v[168:169] op_sel_hi:[1,0] neg_lo:[0,1] neg_hi:[0,1]
	v_pk_add_f32 v[86:87], v[86:87], v[168:169] op_sel_hi:[1,0] neg_lo:[0,1] neg_hi:[0,1]
	v_pk_mul_f32 v[88:89], v[168:169], v[88:89] op_sel:[1,0]
	v_pk_mul_f32 v[90:91], v[168:169], v[90:91] op_sel:[1,0]
	v_pk_mul_f32 v[84:85], v[168:169], v[84:85] op_sel:[1,0]
	v_pk_mul_f32 v[86:87], v[168:169], v[86:87] op_sel:[1,0]
	v_pk_fma_f32 v[88:89], v[140:141], v[88:89], v[144:145]
	v_pk_fma_f32 v[90:91], v[142:143], v[90:91], v[146:147]
	v_pk_fma_f32 v[84:85], v[132:133], v[84:85], v[136:137]
	v_pk_fma_f32 v[86:87], v[134:135], v[86:87], v[138:139]
	v_cvt_pk_f16_f32 v170, v88, v89
	v_cvt_pk_f16_f32 v171, v90, v91
	v_cvt_pk_f16_f32 v172, v84, v85
	v_cvt_pk_f16_f32 v173, v86, v87
	v_add_u32_e32 v170, 0x20002, v170
	v_add_u32_e32 v171, 0x20002, v171
	v_add_u32_e32 v172, 0x20002, v172
	v_add_u32_e32 v173, 0x20002, v173
	v_and_b32_e32 v170, 0xfffcfffc, v170
	v_and_b32_e32 v171, 0xfffcfffc, v171
	v_and_b32_e32 v172, 0xfffcfffc, v172
	v_and_b32_e32 v173, 0xfffcfffc, v173
	global_store_dwordx4 v[176:177], v[170:173], off offset:256
	v_cvt_pk_fp8_f32 v174, v88, v89
	v_cvt_pk_fp8_f32 v175, v84, v85
	v_cvt_pk_fp8_f32 v174, v90, v91 op_sel:[0,0,1]
	v_cvt_pk_fp8_f32 v175, v86, v87 op_sel:[0,0,1]
	global_store_dwordx2 v[180:181], v[174:175], off offset:128
	ds_read_b64 v[168:169], v32 offset:9216
	v_add_co_u32_e32 v176, vcc, 0x18000, v166
	v_addc_co_u32_e32 v177, vcc, 0, v167, vcc
	v_add_co_u32_e32 v180, vcc, 0xc000, v178
	v_addc_co_u32_e32 v181, vcc, 0, v179, vcc
	s_waitcnt lgkmcnt(1)
; template <unsigned D> __device__ __forceinline__ u32x4 rd8(u32x4 w) { w.x = rd<D>(w.x); w.y = rd<D>(w.y); w.z = rd<D>(w.z); w.w = rd<D>(w.w); return w; }
; __device__ __forceinline__ u32x4 pk8(const f32x4 v0, const f32x4 v1) { u32x4 w; w.x = pk_f16(v0[0], v0[1]); w.y = pk_f16(v0[2], v0[3]); w.z = pk_f16(v1[0], v1[1]); w.w = pk_f16(v1[2], v1[3]); return w; }
; __device__ __forceinline__ unsigned pk4_fp8(float a, float b, float c, float d) { int w = __builtin_amdgcn_cvt_pk_fp8_f32(a, b, 0, false); w = __builtin_amdgcn_cvt_pk_fp8_f32(c, d, w, true); return (unsigned)w; }
;     __device__ __forceinline__ void fused(f32x4 (&acc)[2][2][4][2], const GUnit& u, int wr, int wc, int fr, int fq, LAS unsigned char* lds, int wid, int lane) const {
;     ...
; #pragma unroll
;         for (int ai = 0; ai < 2; ++ai)
; #pragma unroll
;             for (int m = 0; m < 4; ++m) { const int r = ai * 128 + wr * 64 + m * 16 + fr; const f32x2 sr = S[r]; const size_t row = (size_t)(u.pm * 256 + r);
; #pragma unroll
;                 for (int bj = 0; bj < 2; ++bj) { const int col = gcol0 + bj * 128;
;                     f32x4 y0 = (acc[ai][bj][m][0] - sr.x) * sr.y * gv[bj][0] + bv[bj][0], y1 = (acc[ai][bj][m][1] - sr.x) * sr.y * gv[bj][1] + bv[bj][1];
;                     if (bad) { y0 = (f32x4){qnan, qnan, qnan, qnan}; y1 = y0; }
;                     if (last) { *(f32x4*)(out + row * 1024 + col) = y0; *(f32x4*)(out + row * 1024 + col + 4) = y1; }
;                     else { *(u32x4*)(H16 + row * 1024 + col) = rd8<D_H>(pk8(y0, y1));
;                            if (h8out) { u32x2 q8v; q8v.x = pk4_fp8(y0[0], y0[1], y0[2], y0[3]); q8v.y = pk4_fp8(y1[0], y1[1], y1[2], y1[3]); *(u32x2*)(ws + WS_H8 + row * 1024 + col) = q8v; } } }
	v_cndmask_b32_e64 v165, v229, v165, s[100:101]
	v_pk_add_f32 v[80:81], v[80:81], v[164:165] op_sel_hi:[1,0] neg_lo:[0,1] neg_hi:[0,1]
	v_pk_add_f32 v[82:83], v[82:83], v[164:165] op_sel_hi:[1,0] neg_lo:[0,1] neg_hi:[0,1]
	v_pk_add_f32 v[76:77], v[76:77], v[164:165] op_sel_hi:[1,0] neg_lo:[0,1] neg_hi:[0,1]
	v_pk_add_f32 v[78:79], v[78:79], v[164:165] op_sel_hi:[1,0] neg_lo:[0,1] neg_hi:[0,1]
	v_pk_mul_f32 v[80:81], v[164:165], v[80:81] op_sel:[1,0]
	v_pk_mul_f32 v[82:83], v[164:165], v[82:83] op_sel:[1,0]
	v_pk_mul_f32 v[76:77], v[164:165], v[76:77] op_sel:[1,0]
	v_pk_mul_f32 v[78:79], v[164:165], v[78:79] op_sel:[1,0]
	v_pk_fma_f32 v[80:81], v[160:161], v[80:81], v[156:157]
	v_pk_fma_f32 v[82:83], v[162:163], v[82:83], v[158:159]
	v_pk_fma_f32 v[76:77], v[148:149], v[76:77], v[152:153]
	v_pk_fma_f32 v[78:79], v[150:151], v[78:79], v[154:155]
	v_cvt_pk_f16_f32 v170, v80, v81
	v_cvt_pk_f16_f32 v171, v82, v83
	v_cvt_pk_f16_f32 v172, v76, v77
	v_cvt_pk_f16_f32 v173, v78, v79
	v_add_u32_e32 v170, 0x20002, v170
	v_add_u32_e32 v171, 0x20002, v171
	v_add_u32_e32 v172, 0x20002, v172
	v_add_u32_e32 v173, 0x20002, v173
	v_and_b32_e32 v170, 0xfffcfffc, v170
	v_and_b32_e32 v171, 0xfffcfffc, v171
	v_and_b32_e32 v172, 0xfffcfffc, v172
	v_and_b32_e32 v173, 0xfffcfffc, v173
	global_store_dwordx4 v[176:177], v[170:173], off
	v_cvt_pk_fp8_f32 v174, v80, v81
	v_cvt_pk_fp8_f32 v175, v76, v77
	v_cvt_pk_fp8_f32 v174, v82, v83 op_sel:[0,0,1]
	v_cvt_pk_fp8_f32 v175, v78, v79 op_sel:[0,0,1]
	global_store_dwordx2 v[180:181], v[174:175], off
	v_pk_add_f32 v[72:73], v[72:73], v[164:165] op_sel_hi:[1,0] neg_lo:[0,1] neg_hi:[0,1]
	v_pk_add_f32 v[74:75], v[74:75], v[164:165] op_sel_hi:[1,0] neg_lo:[0,1] neg_hi:[0,1]
	v_pk_add_f32 v[68:69], v[68:69], v[164:165] op_sel_hi:[1,0] neg_lo:[0,1] neg_hi:[0,1]
	v_pk_add_f32 v[70:71], v[70:71], v[164:165] op_sel_hi:[1,0] neg_lo:[0,1] neg_hi:[0,1]
	v_pk_mul_f32 v[72:73], v[164:165], v[72:73] op_sel:[1,0]
	v_pk_mul_f32 v[74:75], v[164:165], v[74:75] op_sel:[1,0]
	v_pk_mul_f32 v[68:69], v[164:165], v[68:69] op_sel:[1,0]
	v_pk_mul_f32 v[70:71], v[164:165], v[70:71] op_sel:[1,0]
	v_pk_fma_f32 v[72:73], v[140:141], v[72:73], v[144:145]
	v_pk_fma_f32 v[74:75], v[142:143], v[74:75], v[146:147]
	v_pk_fma_f32 v[68:69], v[132:133], v[68:69], v[136:137]
	v_pk_fma_f32 v[70:71], v[134:135], v[70:71], v[138:139]
	v_cvt_pk_f16_f32 v170, v72, v73
	v_cvt_pk_f16_f32 v171, v74, v75
	v_cvt_pk_f16_f32 v172, v68, v69
	v_cvt_pk_f16_f32 v173, v70, v71
	v_add_u32_e32 v170, 0x20002, v170
	v_add_u32_e32 v171, 0x20002, v171
	v_add_u32_e32 v172, 0x20002, v172
	v_add_u32_e32 v173, 0x20002, v173
	v_and_b32_e32 v170, 0xfffcfffc, v170
	v_and_b32_e32 v171, 0xfffcfffc, v171
	v_and_b32_e32 v172, 0xfffcfffc, v172
	v_and_b32_e32 v173, 0xfffcfffc, v173
	global_store_dwordx4 v[176:177], v[170:173], off offset:256
	v_cvt_pk_fp8_f32 v174, v72, v73
	v_cvt_pk_fp8_f32 v175, v68, v69
	v_cvt_pk_fp8_f32 v174, v74, v75 op_sel:[0,0,1]
	v_cvt_pk_fp8_f32 v175, v70, v71 op_sel:[0,0,1]
	global_store_dwordx2 v[180:181], v[174:175], off offset:128
	ds_read_b64 v[164:165], v32 offset:9344
	v_add_co_u32_e32 v176, vcc, 0x40000, v166
	v_addc_co_u32_e32 v177, vcc, 0, v167, vcc
	v_add_co_u32_e32 v180, vcc, 0x20000, v178
	v_addc_co_u32_e32 v181, vcc, 0, v179, vcc
	s_waitcnt lgkmcnt(1)
	v_cndmask_b32_e64 v169, v229, v169, s[100:101]
	v_pk_add_f32 v[64:65], v[64:65], v[168:169] op_sel_hi:[1,0] neg_lo:[0,1] neg_hi:[0,1]
	v_pk_add_f32 v[66:67], v[66:67], v[168:169] op_sel_hi:[1,0] neg_lo:[0,1] neg_hi:[0,1]
	v_pk_add_f32 v[60:61], v[60:61], v[168:169] op_sel_hi:[1,0] neg_lo:[0,1] neg_hi:[0,1]
	v_pk_add_f32 v[62:63], v[62:63], v[168:169] op_sel_hi:[1,0] neg_lo:[0,1] neg_hi:[0,1]
	v_pk_mul_f32 v[64:65], v[168:169], v[64:65] op_sel:[1,0]
	v_pk_mul_f32 v[66:67], v[168:169], v[66:67] op_sel:[1,0]
	v_pk_mul_f32 v[60:61], v[168:169], v[60:61] op_sel:[1,0]
	v_pk_mul_f32 v[62:63], v[168:169], v[62:63] op_sel:[1,0]
	v_pk_fma_f32 v[64:65], v[160:161], v[64:65], v[156:157]
	v_pk_fma_f32 v[66:67], v[162:163], v[66:67], v[158:159]
	v_pk_fma_f32 v[60:61], v[148:149], v[60:61], v[152:153]
	v_pk_fma_f32 v[62:63], v[150:151], v[62:63], v[154:155]
	v_cvt_pk_f16_f32 v170, v64, v65
	v_cvt_pk_f16_f32 v171, v66, v67
	v_cvt_pk_f16_f32 v172, v60, v61
	v_cvt_pk_f16_f32 v173, v62, v63
	v_add_u32_e32 v170, 0x20002, v170
	v_add_u32_e32 v171, 0x20002, v171
	v_add_u32_e32 v172, 0x20002, v172
	v_add_u32_e32 v173, 0x20002, v173
	v_and_b32_e32 v170, 0xfffcfffc, v170
	v_and_b32_e32 v171, 0xfffcfffc, v171
	v_and_b32_e32 v172, 0xfffcfffc, v172
	v_and_b32_e32 v173, 0xfffcfffc, v173
	global_store_dwordx4 v[176:177], v[170:173], off
	v_cvt_pk_fp8_f32 v174, v64, v65
	v_cvt_pk_fp8_f32 v175, v60, v61
	v_cvt_pk_fp8_f32 v174, v66, v67 op_sel:[0,0,1]
	v_cvt_pk_fp8_f32 v175, v62, v63 op_sel:[0,0,1]
	global_store_dwordx2 v[180:181], v[174:175], off
	v_pk_add_f32 v[56:57], v[56:57], v[168:169] op_sel_hi:[1,0] neg_lo:[0,1] neg_hi:[0,1]
	v_pk_add_f32 v[58:59], v[58:59], v[168:169] op_sel_hi:[1,0] neg_lo:[0,1] neg_hi:[0,1]
	v_pk_add_f32 v[52:53], v[52:53], v[168:169] op_sel_hi:[1,0] neg_lo:[0,1] neg_hi:[0,1]
	v_pk_add_f32 v[54:55], v[54:55], v[168:169] op_sel_hi:[1,0] neg_lo:[0,1] neg_hi:[0,1]
	v_pk_mul_f32 v[56:57], v[168:169], v[56:57] op_sel:[1,0]
	v_pk_mul_f32 v[58:59], v[168:169], v[58:59] op_sel:[1,0]
	v_pk_mul_f32 v[52:53], v[168:169], v[52:53] op_sel:[1,0]
	v_pk_mul_f32 v[54:55], v[168:169], v[54:55] op_sel:[1,0]
	v_pk_fma_f32 v[56:57], v[140:141], v[56:57], v[144:145]
	v_pk_fma_f32 v[58:59], v[142:143], v[58:59], v[146:147]
	v_pk_fma_f32 v[52:53], v[132:133], v[52:53], v[136:137]
	v_pk_fma_f32 v[54:55], v[134:135], v[54:55], v[138:139]
	v_cvt_pk_f16_f32 v170, v56, v57
	v_cvt_pk_f16_f32 v171, v58, v59
	v_cvt_pk_f16_f32 v172, v52, v53
	v_cvt_pk_f16_f32 v173, v54, v55
	v_add_u32_e32 v170, 0x20002, v170
	v_add_u32_e32 v171, 0x20002, v171
	v_add_u32_e32 v172, 0x20002, v172
	v_add_u32_e32 v173, 0x20002, v173
	v_and_b32_e32 v170, 0xfffcfffc, v170
	v_and_b32_e32 v171, 0xfffcfffc, v171
	v_and_b32_e32 v172, 0xfffcfffc, v172
	v_and_b32_e32 v173, 0xfffcfffc, v173
	global_store_dwordx4 v[176:177], v[170:173], off offset:256
	v_cvt_pk_fp8_f32 v174, v56, v57
	v_cvt_pk_fp8_f32 v175, v52, v53
	v_cvt_pk_fp8_f32 v174, v58, v59 op_sel:[0,0,1]
	v_cvt_pk_fp8_f32 v175, v54, v55 op_sel:[0,0,1]
	global_store_dwordx2 v[180:181], v[174:175], off offset:128
	ds_read_b64 v[168:169], v32 offset:9472
	v_add_co_u32_e32 v176, vcc, 0x48000, v166
	v_addc_co_u32_e32 v177, vcc, 0, v167, vcc
	v_add_co_u32_e32 v180, vcc, 0x24000, v178
	v_addc_co_u32_e32 v181, vcc, 0, v179, vcc
	s_waitcnt lgkmcnt(1)
; template <unsigned D> __device__ __forceinline__ u32x4 rd8(u32x4 w) { w.x = rd<D>(w.x); w.y = rd<D>(w.y); w.z = rd<D>(w.z); w.w = rd<D>(w.w); return w; }
; __device__ __forceinline__ u32x4 pk8(const f32x4 v0, const f32x4 v1) { u32x4 w; w.x = pk_f16(v0[0], v0[1]); w.y = pk_f16(v0[2], v0[3]); w.z = pk_f16(v1[0], v1[1]); w.w = pk_f16(v1[2], v1[3]); return w; }
; __device__ __forceinline__ unsigned pk4_fp8(float a, float b, float c, float d) { int w = __builtin_amdgcn_cvt_pk_fp8_f32(a, b, 0, false); w = __builtin_amdgcn_cvt_pk_fp8_f32(c, d, w, true); return (unsigned)w; }
;     __device__ __forceinline__ void fused(f32x4 (&acc)[2][2][4][2], const GUnit& u, int wr, int wc, int fr, int fq, LAS unsigned char* lds, int wid, int lane) const {
;     ...
; #pragma unroll
;         for (int ai = 0; ai < 2; ++ai)
; #pragma unroll
;             for (int m = 0; m < 4; ++m) { const int r = ai * 128 + wr * 64 + m * 16 + fr; const f32x2 sr = S[r]; const size_t row = (size_t)(u.pm * 256 + r);
; #pragma unroll
;                 for (int bj = 0; bj < 2; ++bj) { const int col = gcol0 + bj * 128;
;                     f32x4 y0 = (acc[ai][bj][m][0] - sr.x) * sr.y * gv[bj][0] + bv[bj][0], y1 = (acc[ai][bj][m][1] - sr.x) * sr.y * gv[bj][1] + bv[bj][1];
;                     if (bad) { y0 = (f32x4){qnan, qnan, qnan, qnan}; y1 = y0; }
;                     if (last) { *(f32x4*)(out + row * 1024 + col) = y0; *(f32x4*)(out + row * 1024 + col + 4) = y1; }
;                     else { *(u32x4*)(H16 + row * 1024 + col) = rd8<D_H>(pk8(y0, y1));
;                            if (h8out) { u32x2 q8v; q8v.x = pk4_fp8(y0[0], y0[1], y0[2], y0[3]); q8v.y = pk4_fp8(y1[0], y1[1], y1[2], y1[3]); *(u32x2*)(ws + WS_H8 + row * 1024 + col) = q8v; } } }
	v_cndmask_b32_e64 v165, v229, v165, s[100:101]
	v_pk_add_f32 v[48:49], v[48:49], v[164:165] op_sel_hi:[1,0] neg_lo:[0,1] neg_hi:[0,1]
	v_pk_add_f32 v[50:51], v[50:51], v[164:165] op_sel_hi:[1,0] neg_lo:[0,1] neg_hi:[0,1]
	v_pk_add_f32 v[44:45], v[44:45], v[164:165] op_sel_hi:[1,0] neg_lo:[0,1] neg_hi:[0,1]
	v_pk_add_f32 v[46:47], v[46:47], v[164:165] op_sel_hi:[1,0] neg_lo:[0,1] neg_hi:[0,1]
	v_pk_mul_f32 v[48:49], v[164:165], v[48:49] op_sel:[1,0]
	v_pk_mul_f32 v[50:51], v[164:165], v[50:51] op_sel:[1,0]
	v_pk_mul_f32 v[44:45], v[164:165], v[44:45] op_sel:[1,0]
	v_pk_mul_f32 v[46:47], v[164:165], v[46:47] op_sel:[1,0]
	v_pk_fma_f32 v[48:49], v[160:161], v[48:49], v[156:157]
	v_pk_fma_f32 v[50:51], v[162:163], v[50:51], v[158:159]
	v_pk_fma_f32 v[44:45], v[148:149], v[44:45], v[152:153]
	v_pk_fma_f32 v[46:47], v[150:151], v[46:47], v[154:155]
	v_cvt_pk_f16_f32 v170, v48, v49
	v_cvt_pk_f16_f32 v171, v50, v51
	v_cvt_pk_f16_f32 v172, v44, v45
	v_cvt_pk_f16_f32 v173, v46, v47
	v_add_u32_e32 v170, 0x20002, v170
	v_add_u32_e32 v171, 0x20002, v171
	v_add_u32_e32 v172, 0x20002, v172
	v_add_u32_e32 v173, 0x20002, v173
	v_and_b32_e32 v170, 0xfffcfffc, v170
	v_and_b32_e32 v171, 0xfffcfffc, v171
	v_and_b32_e32 v172, 0xfffcfffc, v172
	v_and_b32_e32 v173, 0xfffcfffc, v173
	global_store_dwordx4 v[176:177], v[170:173], off
	v_cvt_pk_fp8_f32 v174, v48, v49
	v_cvt_pk_fp8_f32 v175, v44, v45
	v_cvt_pk_fp8_f32 v174, v50, v51 op_sel:[0,0,1]
	v_cvt_pk_fp8_f32 v175, v46, v47 op_sel:[0,0,1]
	global_store_dwordx2 v[180:181], v[174:175], off
	v_pk_add_f32 v[40:41], v[40:41], v[164:165] op_sel_hi:[1,0] neg_lo:[0,1] neg_hi:[0,1]
	v_pk_add_f32 v[42:43], v[42:43], v[164:165] op_sel_hi:[1,0] neg_lo:[0,1] neg_hi:[0,1]
	v_pk_add_f32 v[36:37], v[36:37], v[164:165] op_sel_hi:[1,0] neg_lo:[0,1] neg_hi:[0,1]
	v_pk_add_f32 v[38:39], v[38:39], v[164:165] op_sel_hi:[1,0] neg_lo:[0,1] neg_hi:[0,1]
	v_pk_mul_f32 v[40:41], v[164:165], v[40:41] op_sel:[1,0]
	v_pk_mul_f32 v[42:43], v[164:165], v[42:43] op_sel:[1,0]
	v_pk_mul_f32 v[36:37], v[164:165], v[36:37] op_sel:[1,0]
	v_pk_mul_f32 v[38:39], v[164:165], v[38:39] op_sel:[1,0]
	v_pk_fma_f32 v[40:41], v[140:141], v[40:41], v[144:145]
	v_pk_fma_f32 v[42:43], v[142:143], v[42:43], v[146:147]
	v_pk_fma_f32 v[36:37], v[132:133], v[36:37], v[136:137]
	v_pk_fma_f32 v[38:39], v[134:135], v[38:39], v[138:139]
	v_cvt_pk_f16_f32 v170, v40, v41
	v_cvt_pk_f16_f32 v171, v42, v43
	v_cvt_pk_f16_f32 v172, v36, v37
	v_cvt_pk_f16_f32 v173, v38, v39
	v_add_u32_e32 v170, 0x20002, v170
	v_add_u32_e32 v171, 0x20002, v171
	v_add_u32_e32 v172, 0x20002, v172
	v_add_u32_e32 v173, 0x20002, v173
	v_and_b32_e32 v170, 0xfffcfffc, v170
	v_and_b32_e32 v171, 0xfffcfffc, v171
	v_and_b32_e32 v172, 0xfffcfffc, v172
	v_and_b32_e32 v173, 0xfffcfffc, v173
	global_store_dwordx4 v[176:177], v[170:173], off offset:256
	v_cvt_pk_fp8_f32 v174, v40, v41
	v_cvt_pk_fp8_f32 v175, v36, v37
	v_cvt_pk_fp8_f32 v174, v42, v43 op_sel:[0,0,1]
	v_cvt_pk_fp8_f32 v175, v38, v39 op_sel:[0,0,1]
	global_store_dwordx2 v[180:181], v[174:175], off offset:128
	ds_read_b64 v[164:165], v32 offset:9600
	v_add_co_u32_e32 v176, vcc, 0x50000, v166
	v_addc_co_u32_e32 v177, vcc, 0, v167, vcc
	v_add_co_u32_e32 v180, vcc, 0x28000, v178
	v_addc_co_u32_e32 v181, vcc, 0, v179, vcc
	s_waitcnt lgkmcnt(1)
	v_cndmask_b32_e64 v169, v229, v169, s[100:101]
	v_pk_add_f32 v[28:29], v[28:29], v[168:169] op_sel_hi:[1,0] neg_lo:[0,1] neg_hi:[0,1]
	v_pk_add_f32 v[30:31], v[30:31], v[168:169] op_sel_hi:[1,0] neg_lo:[0,1] neg_hi:[0,1]
	v_pk_add_f32 v[24:25], v[24:25], v[168:169] op_sel_hi:[1,0] neg_lo:[0,1] neg_hi:[0,1]
	v_pk_add_f32 v[26:27], v[26:27], v[168:169] op_sel_hi:[1,0] neg_lo:[0,1] neg_hi:[0,1]
	v_pk_mul_f32 v[28:29], v[168:169], v[28:29] op_sel:[1,0]
	v_pk_mul_f32 v[30:31], v[168:169], v[30:31] op_sel:[1,0]
	v_pk_mul_f32 v[24:25], v[168:169], v[24:25] op_sel:[1,0]
	v_pk_mul_f32 v[26:27], v[168:169], v[26:27] op_sel:[1,0]
	v_pk_fma_f32 v[28:29], v[160:161], v[28:29], v[156:157]
	v_pk_fma_f32 v[30:31], v[162:163], v[30:31], v[158:159]
	v_pk_fma_f32 v[24:25], v[148:149], v[24:25], v[152:153]
	v_pk_fma_f32 v[26:27], v[150:151], v[26:27], v[154:155]
	v_cvt_pk_f16_f32 v170, v28, v29
	v_cvt_pk_f16_f32 v171, v30, v31
	v_cvt_pk_f16_f32 v172, v24, v25
	v_cvt_pk_f16_f32 v173, v26, v27
	v_add_u32_e32 v170, 0x20002, v170
	v_add_u32_e32 v171, 0x20002, v171
	v_add_u32_e32 v172, 0x20002, v172
	v_add_u32_e32 v173, 0x20002, v173
	v_and_b32_e32 v170, 0xfffcfffc, v170
	v_and_b32_e32 v171, 0xfffcfffc, v171
	v_and_b32_e32 v172, 0xfffcfffc, v172
	v_and_b32_e32 v173, 0xfffcfffc, v173
	global_store_dwordx4 v[176:177], v[170:173], off
	v_cvt_pk_fp8_f32 v174, v28, v29
	v_cvt_pk_fp8_f32 v175, v24, v25
	v_cvt_pk_fp8_f32 v174, v30, v31 op_sel:[0,0,1]
	v_cvt_pk_fp8_f32 v175, v26, v27 op_sel:[0,0,1]
	global_store_dwordx2 v[180:181], v[174:175], off
	v_pk_add_f32 v[20:21], v[20:21], v[168:169] op_sel_hi:[1,0] neg_lo:[0,1] neg_hi:[0,1]
	v_pk_add_f32 v[22:23], v[22:23], v[168:169] op_sel_hi:[1,0] neg_lo:[0,1] neg_hi:[0,1]
	v_pk_add_f32 v[16:17], v[16:17], v[168:169] op_sel_hi:[1,0] neg_lo:[0,1] neg_hi:[0,1]
	v_pk_add_f32 v[18:19], v[18:19], v[168:169] op_sel_hi:[1,0] neg_lo:[0,1] neg_hi:[0,1]
	v_pk_mul_f32 v[20:21], v[168:169], v[20:21] op_sel:[1,0]
	v_pk_mul_f32 v[22:23], v[168:169], v[22:23] op_sel:[1,0]
	v_pk_mul_f32 v[16:17], v[168:169], v[16:17] op_sel:[1,0]
	v_pk_mul_f32 v[18:19], v[168:169], v[18:19] op_sel:[1,0]
	v_pk_fma_f32 v[20:21], v[140:141], v[20:21], v[144:145]
	v_pk_fma_f32 v[22:23], v[142:143], v[22:23], v[146:147]
	v_pk_fma_f32 v[16:17], v[132:133], v[16:17], v[136:137]
	v_pk_fma_f32 v[18:19], v[134:135], v[18:19], v[138:139]
	v_cvt_pk_f16_f32 v170, v20, v21
	v_cvt_pk_f16_f32 v171, v22, v23
	v_cvt_pk_f16_f32 v172, v16, v17
	v_cvt_pk_f16_f32 v173, v18, v19
	v_add_u32_e32 v170, 0x20002, v170
	v_add_u32_e32 v171, 0x20002, v171
	v_add_u32_e32 v172, 0x20002, v172
	v_add_u32_e32 v173, 0x20002, v173
	v_and_b32_e32 v170, 0xfffcfffc, v170
	v_and_b32_e32 v171, 0xfffcfffc, v171
	v_and_b32_e32 v172, 0xfffcfffc, v172
	v_and_b32_e32 v173, 0xfffcfffc, v173
	global_store_dwordx4 v[176:177], v[170:173], off offset:256
	v_cvt_pk_fp8_f32 v174, v20, v21
	v_cvt_pk_fp8_f32 v175, v16, v17
	v_cvt_pk_fp8_f32 v174, v22, v23 op_sel:[0,0,1]
	v_cvt_pk_fp8_f32 v175, v18, v19 op_sel:[0,0,1]
	global_store_dwordx2 v[180:181], v[174:175], off offset:128
	v_add_co_u32_e32 v176, vcc, 0x58000, v166
	v_addc_co_u32_e32 v177, vcc, 0, v167, vcc
	v_add_co_u32_e32 v180, vcc, 0x2c000, v178
	v_addc_co_u32_e32 v181, vcc, 0, v179, vcc
	s_waitcnt lgkmcnt(0)
; template <unsigned D> __device__ __forceinline__ u32x4 rd8(u32x4 w) { w.x = rd<D>(w.x); w.y = rd<D>(w.y); w.z = rd<D>(w.z); w.w = rd<D>(w.w); return w; }
; __device__ __forceinline__ u32x4 pk8(const f32x4 v0, const f32x4 v1) { u32x4 w; w.x = pk_f16(v0[0], v0[1]); w.y = pk_f16(v0[2], v0[3]); w.z = pk_f16(v1[0], v1[1]); w.w = pk_f16(v1[2], v1[3]); return w; }
; __device__ __forceinline__ unsigned pk4_fp8(float a, float b, float c, float d) { int w = __builtin_amdgcn_cvt_pk_fp8_f32(a, b, 0, false); w = __builtin_amdgcn_cvt_pk_fp8_f32(c, d, w, true); return (unsigned)w; }
;     __device__ __forceinline__ void fused(f32x4 (&acc)[2][2][4][2], const GUnit& u, int wr, int wc, int fr, int fq, LAS unsigned char* lds, int wid, int lane) const {
;     ...
; #pragma unroll
;         for (int ai = 0; ai < 2; ++ai)
; #pragma unroll
;             for (int m = 0; m < 4; ++m) { const int r = ai * 128 + wr * 64 + m * 16 + fr; const f32x2 sr = S[r]; const size_t row = (size_t)(u.pm * 256 + r);
; #pragma unroll
;                 for (int bj = 0; bj < 2; ++bj) { const int col = gcol0 + bj * 128;
;                     f32x4 y0 = (acc[ai][bj][m][0] - sr.x) * sr.y * gv[bj][0] + bv[bj][0], y1 = (acc[ai][bj][m][1] - sr.x) * sr.y * gv[bj][1] + bv[bj][1];
;                     if (bad) { y0 = (f32x4){qnan, qnan, qnan, qnan}; y1 = y0; }
;                     if (last) { *(f32x4*)(out + row * 1024 + col) = y0; *(f32x4*)(out + row * 1024 + col + 4) = y1; }
;                     else { *(u32x4*)(H16 + row * 1024 + col) = rd8<D_H>(pk8(y0, y1));
;                            if (h8out) { u32x2 q8v; q8v.x = pk4_fp8(y0[0], y0[1], y0[2], y0[3]); q8v.y = pk4_fp8(y1[0], y1[1], y1[2], y1[3]); *(u32x2*)(ws + WS_H8 + row * 1024 + col) = q8v; } } }
	v_cndmask_b32_e64 v165, v229, v165, s[100:101]
	v_pk_add_f32 v[12:13], v[12:13], v[164:165] op_sel_hi:[1,0] neg_lo:[0,1] neg_hi:[0,1]
	v_pk_add_f32 v[14:15], v[14:15], v[164:165] op_sel_hi:[1,0] neg_lo:[0,1] neg_hi:[0,1]
	v_pk_add_f32 v[8:9], v[8:9], v[164:165] op_sel_hi:[1,0] neg_lo:[0,1] neg_hi:[0,1]
	v_pk_add_f32 v[10:11], v[10:11], v[164:165] op_sel_hi:[1,0] neg_lo:[0,1] neg_hi:[0,1]
	v_pk_mul_f32 v[12:13], v[164:165], v[12:13] op_sel:[1,0]
	v_pk_mul_f32 v[14:15], v[164:165], v[14:15] op_sel:[1,0]
	v_pk_mul_f32 v[8:9], v[164:165], v[8:9] op_sel:[1,0]
	v_pk_mul_f32 v[10:11], v[164:165], v[10:11] op_sel:[1,0]
	v_pk_fma_f32 v[12:13], v[160:161], v[12:13], v[156:157]
	v_pk_fma_f32 v[14:15], v[162:163], v[14:15], v[158:159]
	v_pk_fma_f32 v[8:9], v[148:149], v[8:9], v[152:153]
	v_pk_fma_f32 v[10:11], v[150:151], v[10:11], v[154:155]
	v_cvt_pk_f16_f32 v170, v12, v13
	v_cvt_pk_f16_f32 v171, v14, v15
	v_cvt_pk_f16_f32 v172, v8, v9
	v_cvt_pk_f16_f32 v173, v10, v11
	v_add_u32_e32 v170, 0x20002, v170
	v_add_u32_e32 v171, 0x20002, v171
	v_add_u32_e32 v172, 0x20002, v172
	v_add_u32_e32 v173, 0x20002, v173
	v_and_b32_e32 v170, 0xfffcfffc, v170
	v_and_b32_e32 v171, 0xfffcfffc, v171
	v_and_b32_e32 v172, 0xfffcfffc, v172
	v_and_b32_e32 v173, 0xfffcfffc, v173
	global_store_dwordx4 v[176:177], v[170:173], off
	v_cvt_pk_fp8_f32 v174, v12, v13
	v_cvt_pk_fp8_f32 v175, v8, v9
	v_cvt_pk_fp8_f32 v174, v14, v15 op_sel:[0,0,1]
	v_cvt_pk_fp8_f32 v175, v10, v11 op_sel:[0,0,1]
	global_store_dwordx2 v[180:181], v[174:175], off
	v_pk_add_f32 v[4:5], v[4:5], v[164:165] op_sel_hi:[1,0] neg_lo:[0,1] neg_hi:[0,1]
	v_pk_add_f32 v[6:7], v[6:7], v[164:165] op_sel_hi:[1,0] neg_lo:[0,1] neg_hi:[0,1]
	v_pk_add_f32 v[0:1], v[0:1], v[164:165] op_sel_hi:[1,0] neg_lo:[0,1] neg_hi:[0,1]
	v_pk_add_f32 v[2:3], v[2:3], v[164:165] op_sel_hi:[1,0] neg_lo:[0,1] neg_hi:[0,1]
	v_pk_mul_f32 v[4:5], v[164:165], v[4:5] op_sel:[1,0]
	v_pk_mul_f32 v[6:7], v[164:165], v[6:7] op_sel:[1,0]
	v_pk_mul_f32 v[0:1], v[164:165], v[0:1] op_sel:[1,0]
	v_pk_mul_f32 v[2:3], v[164:165], v[2:3] op_sel:[1,0]
	v_pk_fma_f32 v[4:5], v[140:141], v[4:5], v[144:145]
	v_pk_fma_f32 v[6:7], v[142:143], v[6:7], v[146:147]
	v_pk_fma_f32 v[0:1], v[132:133], v[0:1], v[136:137]
	v_pk_fma_f32 v[2:3], v[134:135], v[2:3], v[138:139]
	v_cvt_pk_f16_f32 v170, v4, v5
	v_cvt_pk_f16_f32 v171, v6, v7
	v_cvt_pk_f16_f32 v172, v0, v1
	v_cvt_pk_f16_f32 v173, v2, v3
	v_add_u32_e32 v170, 0x20002, v170
	v_add_u32_e32 v171, 0x20002, v171
	v_add_u32_e32 v172, 0x20002, v172
	v_add_u32_e32 v173, 0x20002, v173
	v_and_b32_e32 v170, 0xfffcfffc, v170
	v_and_b32_e32 v171, 0xfffcfffc, v171
	v_and_b32_e32 v172, 0xfffcfffc, v172
	v_and_b32_e32 v173, 0xfffcfffc, v173
	global_store_dwordx4 v[176:177], v[170:173], off offset:256
	v_cvt_pk_fp8_f32 v174, v4, v5
	v_cvt_pk_fp8_f32 v175, v0, v1
	v_cvt_pk_fp8_f32 v174, v6, v7 op_sel:[0,0,1]
	v_cvt_pk_fp8_f32 v175, v2, v3 op_sel:[0,0,1]
	global_store_dwordx2 v[180:181], v[174:175], off offset:128
	v_mov_b32_e32 v233, v226
	s_branch .LBB0_567
.Lap_d:
	ds_read_b64 v[168:169], v32 offset:8192
	ds_read_b64 v[164:165], v32 offset:8320
	s_waitcnt vmcnt(0) lgkmcnt(1)
	v_cndmask_b32_e64 v169, v229, v169, s[100:101]
	v_pk_add_f32 v[128:129], v[128:129], v[168:169] op_sel_hi:[1,0] neg_lo:[0,1] neg_hi:[0,1]
	v_pk_add_f32 v[130:131], v[130:131], v[168:169] op_sel_hi:[1,0] neg_lo:[0,1] neg_hi:[0,1]
	v_pk_add_f32 v[124:125], v[124:125], v[168:169] op_sel_hi:[1,0] neg_lo:[0,1] neg_hi:[0,1]
	v_pk_add_f32 v[126:127], v[126:127], v[168:169] op_sel_hi:[1,0] neg_lo:[0,1] neg_hi:[0,1]
	v_pk_mul_f32 v[128:129], v[168:169], v[128:129] op_sel:[1,0]
	v_pk_mul_f32 v[130:131], v[168:169], v[130:131] op_sel:[1,0]
	v_pk_mul_f32 v[124:125], v[168:169], v[124:125] op_sel:[1,0]
	v_pk_mul_f32 v[126:127], v[168:169], v[126:127] op_sel:[1,0]
	v_pk_fma_f32 v[128:129], v[160:161], v[128:129], v[156:157]
	v_pk_fma_f32 v[130:131], v[162:163], v[130:131], v[158:159]
	v_pk_fma_f32 v[124:125], v[148:149], v[124:125], v[152:153]
	v_pk_fma_f32 v[126:127], v[150:151], v[126:127], v[154:155]
	v_cvt_pk_f16_f32 v170, v128, v129
	v_cvt_pk_f16_f32 v171, v130, v131
	v_cvt_pk_f16_f32 v172, v124, v125
	v_cvt_pk_f16_f32 v173, v126, v127
	v_add_u32_e32 v170, 0x20002, v170
	v_add_u32_e32 v171, 0x20002, v171
	v_add_u32_e32 v172, 0x20002, v172
	v_add_u32_e32 v173, 0x20002, v173
	v_and_b32_e32 v170, 0xfffcfffc, v170
	v_and_b32_e32 v171, 0xfffcfffc, v171
	v_and_b32_e32 v172, 0xfffcfffc, v172
	v_and_b32_e32 v173, 0xfffcfffc, v173
	global_store_dwordx4 v[166:167], v[170:173], off
	v_pk_add_f32 v[120:121], v[120:121], v[168:169] op_sel_hi:[1,0] neg_lo:[0,1] neg_hi:[0,1]
	v_pk_add_f32 v[122:123], v[122:123], v[168:169] op_sel_hi:[1,0] neg_lo:[0,1] neg_hi:[0,1]
	v_pk_add_f32 v[116:117], v[116:117], v[168:169] op_sel_hi:[1,0] neg_lo:[0,1] neg_hi:[0,1]
	v_pk_add_f32 v[118:119], v[118:119], v[168:169] op_sel_hi:[1,0] neg_lo:[0,1] neg_hi:[0,1]
	v_pk_mul_f32 v[120:121], v[168:169], v[120:121] op_sel:[1,0]
	v_pk_mul_f32 v[122:123], v[168:169], v[122:123] op_sel:[1,0]
	v_pk_mul_f32 v[116:117], v[168:169], v[116:117] op_sel:[1,0]
	v_pk_mul_f32 v[118:119], v[168:169], v[118:119] op_sel:[1,0]
	v_pk_fma_f32 v[120:121], v[140:141], v[120:121], v[144:145]
	v_pk_fma_f32 v[122:123], v[142:143], v[122:123], v[146:147]
	v_pk_fma_f32 v[116:117], v[132:133], v[116:117], v[136:137]
	v_pk_fma_f32 v[118:119], v[134:135], v[118:119], v[138:139]
	v_cvt_pk_f16_f32 v170, v120, v121
	v_cvt_pk_f16_f32 v171, v122, v123
	v_cvt_pk_f16_f32 v172, v116, v117
	v_cvt_pk_f16_f32 v173, v118, v119
	v_add_u32_e32 v170, 0x20002, v170
	v_add_u32_e32 v171, 0x20002, v171
	v_add_u32_e32 v172, 0x20002, v172
	v_add_u32_e32 v173, 0x20002, v173
	v_and_b32_e32 v170, 0xfffcfffc, v170
	v_and_b32_e32 v171, 0xfffcfffc, v171
	v_and_b32_e32 v172, 0xfffcfffc, v172
	v_and_b32_e32 v173, 0xfffcfffc, v173
	global_store_dwordx4 v[166:167], v[170:173], off offset:256
	ds_read_b64 v[168:169], v32 offset:8448
	v_add_co_u32_e32 v176, vcc, 0x8000, v166
	v_addc_co_u32_e32 v177, vcc, 0, v167, vcc
	s_waitcnt lgkmcnt(1)
; template <unsigned D> __device__ __forceinline__ u32x4 rd8(u32x4 w) { w.x = rd<D>(w.x); w.y = rd<D>(w.y); w.z = rd<D>(w.z); w.w = rd<D>(w.w); return w; }
; __device__ __forceinline__ u32x4 pk8(const f32x4 v0, const f32x4 v1) { u32x4 w; w.x = pk_f16(v0[0], v0[1]); w.y = pk_f16(v0[2], v0[3]); w.z = pk_f16(v1[0], v1[1]); w.w = pk_f16(v1[2], v1[3]); return w; }
; __device__ __forceinline__ unsigned pk4_fp8(float a, float b, float c, float d) { int w = __builtin_amdgcn_cvt_pk_fp8_f32(a, b, 0, false); w = __builtin_amdgcn_cvt_pk_fp8_f32(c, d, w, true); return (unsigned)w; }
;     __device__ __forceinline__ void fused(f32x4 (&acc)[2][2][4][2], const GUnit& u, int wr, int wc, int fr, int fq, LAS unsigned char* lds, int wid, int lane) const {
;     ...
; #pragma unroll
;         for (int ai = 0; ai < 2; ++ai)
; #pragma unroll
;             for (int m = 0; m < 4; ++m) { const int r = ai * 128 + wr * 64 + m * 16 + fr; const f32x2 sr = S[r]; const size_t row = (size_t)(u.pm * 256 + r);
; #pragma unroll
;                 for (int bj = 0; bj < 2; ++bj) { const int col = gcol0 + bj * 128;
;                     f32x4 y0 = (acc[ai][bj][m][0] - sr.x) * sr.y * gv[bj][0] + bv[bj][0], y1 = (acc[ai][bj][m][1] - sr.x) * sr.y * gv[bj][1] + bv[bj][1];
;                     if (bad) { y0 = (f32x4){qnan, qnan, qnan, qnan}; y1 = y0; }
;                     if (last) { *(f32x4*)(out + row * 1024 + col) = y0; *(f32x4*)(out + row * 1024 + col + 4) = y1; }
;                     else { *(u32x4*)(H16 + row * 1024 + col) = rd8<D_H>(pk8(y0, y1));
;                            if (h8out) { u32x2 q8v; q8v.x = pk4_fp8(y0[0], y0[1], y0[2], y0[3]); q8v.y = pk4_fp8(y1[0], y1[1], y1[2], y1[3]); *(u32x2*)(ws + WS_H8 + row * 1024 + col) = q8v; } } }
	v_cndmask_b32_e64 v165, v229, v165, s[100:101]
	v_pk_add_f32 v[112:113], v[112:113], v[164:165] op_sel_hi:[1,0] neg_lo:[0,1] neg_hi:[0,1]
	v_pk_add_f32 v[114:115], v[114:115], v[164:165] op_sel_hi:[1,0] neg_lo:[0,1] neg_hi:[0,1]
	v_pk_add_f32 v[108:109], v[108:109], v[164:165] op_sel_hi:[1,0] neg_lo:[0,1] neg_hi:[0,1]
	v_pk_add_f32 v[110:111], v[110:111], v[164:165] op_sel_hi:[1,0] neg_lo:[0,1] neg_hi:[0,1]
	v_pk_mul_f32 v[112:113], v[164:165], v[112:113] op_sel:[1,0]
	v_pk_mul_f32 v[114:115], v[164:165], v[114:115] op_sel:[1,0]
	v_pk_mul_f32 v[108:109], v[164:165], v[108:109] op_sel:[1,0]
	v_pk_mul_f32 v[110:111], v[164:165], v[110:111] op_sel:[1,0]
	v_pk_fma_f32 v[112:113], v[160:161], v[112:113], v[156:157]
	v_pk_fma_f32 v[114:115], v[162:163], v[114:115], v[158:159]
	v_pk_fma_f32 v[108:109], v[148:149], v[108:109], v[152:153]
	v_pk_fma_f32 v[110:111], v[150:151], v[110:111], v[154:155]
	v_cvt_pk_f16_f32 v170, v112, v113
	v_cvt_pk_f16_f32 v171, v114, v115
	v_cvt_pk_f16_f32 v172, v108, v109
	v_cvt_pk_f16_f32 v173, v110, v111
	v_add_u32_e32 v170, 0x20002, v170
	v_add_u32_e32 v171, 0x20002, v171
	v_add_u32_e32 v172, 0x20002, v172
	v_add_u32_e32 v173, 0x20002, v173
	v_and_b32_e32 v170, 0xfffcfffc, v170
	v_and_b32_e32 v171, 0xfffcfffc, v171
	v_and_b32_e32 v172, 0xfffcfffc, v172
	v_and_b32_e32 v173, 0xfffcfffc, v173
	global_store_dwordx4 v[176:177], v[170:173], off
	v_pk_add_f32 v[104:105], v[104:105], v[164:165] op_sel_hi:[1,0] neg_lo:[0,1] neg_hi:[0,1]
	v_pk_add_f32 v[106:107], v[106:107], v[164:165] op_sel_hi:[1,0] neg_lo:[0,1] neg_hi:[0,1]
	v_pk_add_f32 v[100:101], v[100:101], v[164:165] op_sel_hi:[1,0] neg_lo:[0,1] neg_hi:[0,1]
	v_pk_add_f32 v[102:103], v[102:103], v[164:165] op_sel_hi:[1,0] neg_lo:[0,1] neg_hi:[0,1]
	v_pk_mul_f32 v[104:105], v[164:165], v[104:105] op_sel:[1,0]
	v_pk_mul_f32 v[106:107], v[164:165], v[106:107] op_sel:[1,0]
	v_pk_mul_f32 v[100:101], v[164:165], v[100:101] op_sel:[1,0]
	v_pk_mul_f32 v[102:103], v[164:165], v[102:103] op_sel:[1,0]
	v_pk_fma_f32 v[104:105], v[140:141], v[104:105], v[144:145]
	v_pk_fma_f32 v[106:107], v[142:143], v[106:107], v[146:147]
	v_pk_fma_f32 v[100:101], v[132:133], v[100:101], v[136:137]
	v_pk_fma_f32 v[102:103], v[134:135], v[102:103], v[138:139]
	v_cvt_pk_f16_f32 v170, v104, v105
	v_cvt_pk_f16_f32 v171, v106, v107
	v_cvt_pk_f16_f32 v172, v100, v101
	v_cvt_pk_f16_f32 v173, v102, v103
	v_add_u32_e32 v170, 0x20002, v170
	v_add_u32_e32 v171, 0x20002, v171
	v_add_u32_e32 v172, 0x20002, v172
	v_add_u32_e32 v173, 0x20002, v173
	v_and_b32_e32 v170, 0xfffcfffc, v170
	v_and_b32_e32 v171, 0xfffcfffc, v171
	v_and_b32_e32 v172, 0xfffcfffc, v172
	v_and_b32_e32 v173, 0xfffcfffc, v173
	global_store_dwordx4 v[176:177], v[170:173], off offset:256
	ds_read_b64 v[164:165], v32 offset:8576
	v_add_co_u32_e32 v176, vcc, 0x10000, v166
	v_addc_co_u32_e32 v177, vcc, 0, v167, vcc
	s_waitcnt lgkmcnt(1)
	v_cndmask_b32_e64 v169, v229, v169, s[100:101]
	v_pk_add_f32 v[96:97], v[96:97], v[168:169] op_sel_hi:[1,0] neg_lo:[0,1] neg_hi:[0,1]
	v_pk_add_f32 v[98:99], v[98:99], v[168:169] op_sel_hi:[1,0] neg_lo:[0,1] neg_hi:[0,1]
	v_pk_add_f32 v[92:93], v[92:93], v[168:169] op_sel_hi:[1,0] neg_lo:[0,1] neg_hi:[0,1]
	v_pk_add_f32 v[94:95], v[94:95], v[168:169] op_sel_hi:[1,0] neg_lo:[0,1] neg_hi:[0,1]
	v_pk_mul_f32 v[96:97], v[168:169], v[96:97] op_sel:[1,0]
	v_pk_mul_f32 v[98:99], v[168:169], v[98:99] op_sel:[1,0]
	v_pk_mul_f32 v[92:93], v[168:169], v[92:93] op_sel:[1,0]
	v_pk_mul_f32 v[94:95], v[168:169], v[94:95] op_sel:[1,0]
	v_pk_fma_f32 v[96:97], v[160:161], v[96:97], v[156:157]
	v_pk_fma_f32 v[98:99], v[162:163], v[98:99], v[158:159]
	v_pk_fma_f32 v[92:93], v[148:149], v[92:93], v[152:153]
	v_pk_fma_f32 v[94:95], v[150:151], v[94:95], v[154:155]
	v_cvt_pk_f16_f32 v170, v96, v97
	v_cvt_pk_f16_f32 v171, v98, v99
	v_cvt_pk_f16_f32 v172, v92, v93
	v_cvt_pk_f16_f32 v173, v94, v95
	v_add_u32_e32 v170, 0x20002, v170
	v_add_u32_e32 v171, 0x20002, v171
	v_add_u32_e32 v172, 0x20002, v172
	v_add_u32_e32 v173, 0x20002, v173
	v_and_b32_e32 v170, 0xfffcfffc, v170
	v_and_b32_e32 v171, 0xfffcfffc, v171
	v_and_b32_e32 v172, 0xfffcfffc, v172
	v_and_b32_e32 v173, 0xfffcfffc, v173
	global_store_dwordx4 v[176:177], v[170:173], off
	v_pk_add_f32 v[88:89], v[88:89], v[168:169] op_sel_hi:[1,0] neg_lo:[0,1] neg_hi:[0,1]
	v_pk_add_f32 v[90:91], v[90:91], v[168:169] op_sel_hi:[1,0] neg_lo:[0,1] neg_hi:[0,1]
	v_pk_add_f32 v[84:85], v[84:85], v[168:169] op_sel_hi:[1,0] neg_lo:[0,1] neg_hi:[0,1]
	v_pk_add_f32 v[86:87], v[86:87], v[168:169] op_sel_hi:[1,0] neg_lo:[0,1] neg_hi:[0,1]
	v_pk_mul_f32 v[88:89], v[168:169], v[88:89] op_sel:[1,0]
	v_pk_mul_f32 v[90:91], v[168:169], v[90:91] op_sel:[1,0]
	v_pk_mul_f32 v[84:85], v[168:169], v[84:85] op_sel:[1,0]
	v_pk_mul_f32 v[86:87], v[168:169], v[86:87] op_sel:[1,0]
	v_pk_fma_f32 v[88:89], v[140:141], v[88:89], v[144:145]
	v_pk_fma_f32 v[90:91], v[142:143], v[90:91], v[146:147]
	v_pk_fma_f32 v[84:85], v[132:133], v[84:85], v[136:137]
	v_pk_fma_f32 v[86:87], v[134:135], v[86:87], v[138:139]
	v_cvt_pk_f16_f32 v170, v88, v89
	v_cvt_pk_f16_f32 v171, v90, v91
	v_cvt_pk_f16_f32 v172, v84, v85
	v_cvt_pk_f16_f32 v173, v86, v87
	v_add_u32_e32 v170, 0x20002, v170
	v_add_u32_e32 v171, 0x20002, v171
	v_add_u32_e32 v172, 0x20002, v172
	v_add_u32_e32 v173, 0x20002, v173
	v_and_b32_e32 v170, 0xfffcfffc, v170
	v_and_b32_e32 v171, 0xfffcfffc, v171
	v_and_b32_e32 v172, 0xfffcfffc, v172
	v_and_b32_e32 v173, 0xfffcfffc, v173
	global_store_dwordx4 v[176:177], v[170:173], off offset:256
	ds_read_b64 v[168:169], v32 offset:9216
	v_add_co_u32_e32 v176, vcc, 0x18000, v166
	v_addc_co_u32_e32 v177, vcc, 0, v167, vcc
	s_waitcnt lgkmcnt(1)
; template <unsigned D> __device__ __forceinline__ u32x4 rd8(u32x4 w) { w.x = rd<D>(w.x); w.y = rd<D>(w.y); w.z = rd<D>(w.z); w.w = rd<D>(w.w); return w; }
; __device__ __forceinline__ u32x4 pk8(const f32x4 v0, const f32x4 v1) { u32x4 w; w.x = pk_f16(v0[0], v0[1]); w.y = pk_f16(v0[2], v0[3]); w.z = pk_f16(v1[0], v1[1]); w.w = pk_f16(v1[2], v1[3]); return w; }
; __device__ __forceinline__ unsigned pk4_fp8(float a, float b, float c, float d) { int w = __builtin_amdgcn_cvt_pk_fp8_f32(a, b, 0, false); w = __builtin_amdgcn_cvt_pk_fp8_f32(c, d, w, true); return (unsigned)w; }
;     __device__ __forceinline__ void fused(f32x4 (&acc)[2][2][4][2], const GUnit& u, int wr, int wc, int fr, int fq, LAS unsigned char* lds, int wid, int lane) const {
;     ...
; #pragma unroll
;         for (int ai = 0; ai < 2; ++ai)
; #pragma unroll
;             for (int m = 0; m < 4; ++m) { const int r = ai * 128 + wr * 64 + m * 16 + fr; const f32x2 sr = S[r]; const size_t row = (size_t)(u.pm * 256 + r);
; #pragma unroll
;                 for (int bj = 0; bj < 2; ++bj) { const int col = gcol0 + bj * 128;
;                     f32x4 y0 = (acc[ai][bj][m][0] - sr.x) * sr.y * gv[bj][0] + bv[bj][0], y1 = (acc[ai][bj][m][1] - sr.x) * sr.y * gv[bj][1] + bv[bj][1];
;                     if (bad) { y0 = (f32x4){qnan, qnan, qnan, qnan}; y1 = y0; }
;                     if (last) { *(f32x4*)(out + row * 1024 + col) = y0; *(f32x4*)(out + row * 1024 + col + 4) = y1; }
;                     else { *(u32x4*)(H16 + row * 1024 + col) = rd8<D_H>(pk8(y0, y1));
;                            if (h8out) { u32x2 q8v; q8v.x = pk4_fp8(y0[0], y0[1], y0[2], y0[3]); q8v.y = pk4_fp8(y1[0], y1[1], y1[2], y1[3]); *(u32x2*)(ws + WS_H8 + row * 1024 + col) = q8v; } } }
	v_cndmask_b32_e64 v165, v229, v165, s[100:101]
	v_pk_add_f32 v[80:81], v[80:81], v[164:165] op_sel_hi:[1,0] neg_lo:[0,1] neg_hi:[0,1]
	v_pk_add_f32 v[82:83], v[82:83], v[164:165] op_sel_hi:[1,0] neg_lo:[0,1] neg_hi:[0,1]
	v_pk_add_f32 v[76:77], v[76:77], v[164:165] op_sel_hi:[1,0] neg_lo:[0,1] neg_hi:[0,1]
	v_pk_add_f32 v[78:79], v[78:79], v[164:165] op_sel_hi:[1,0] neg_lo:[0,1] neg_hi:[0,1]
	v_pk_mul_f32 v[80:81], v[164:165], v[80:81] op_sel:[1,0]
	v_pk_mul_f32 v[82:83], v[164:165], v[82:83] op_sel:[1,0]
	v_pk_mul_f32 v[76:77], v[164:165], v[76:77] op_sel:[1,0]
	v_pk_mul_f32 v[78:79], v[164:165], v[78:79] op_sel:[1,0]
	v_pk_fma_f32 v[80:81], v[160:161], v[80:81], v[156:157]
	v_pk_fma_f32 v[82:83], v[162:163], v[82:83], v[158:159]
	v_pk_fma_f32 v[76:77], v[148:149], v[76:77], v[152:153]
	v_pk_fma_f32 v[78:79], v[150:151], v[78:79], v[154:155]
	v_cvt_pk_f16_f32 v170, v80, v81
	v_cvt_pk_f16_f32 v171, v82, v83
	v_cvt_pk_f16_f32 v172, v76, v77
	v_cvt_pk_f16_f32 v173, v78, v79
	v_add_u32_e32 v170, 0x20002, v170
	v_add_u32_e32 v171, 0x20002, v171
	v_add_u32_e32 v172, 0x20002, v172
	v_add_u32_e32 v173, 0x20002, v173
	v_and_b32_e32 v170, 0xfffcfffc, v170
	v_and_b32_e32 v171, 0xfffcfffc, v171
	v_and_b32_e32 v172, 0xfffcfffc, v172
	v_and_b32_e32 v173, 0xfffcfffc, v173
	global_store_dwordx4 v[176:177], v[170:173], off
	v_pk_add_f32 v[72:73], v[72:73], v[164:165] op_sel_hi:[1,0] neg_lo:[0,1] neg_hi:[0,1]
	v_pk_add_f32 v[74:75], v[74:75], v[164:165] op_sel_hi:[1,0] neg_lo:[0,1] neg_hi:[0,1]
	v_pk_add_f32 v[68:69], v[68:69], v[164:165] op_sel_hi:[1,0] neg_lo:[0,1] neg_hi:[0,1]
	v_pk_add_f32 v[70:71], v[70:71], v[164:165] op_sel_hi:[1,0] neg_lo:[0,1] neg_hi:[0,1]
	v_pk_mul_f32 v[72:73], v[164:165], v[72:73] op_sel:[1,0]
	v_pk_mul_f32 v[74:75], v[164:165], v[74:75] op_sel:[1,0]
	v_pk_mul_f32 v[68:69], v[164:165], v[68:69] op_sel:[1,0]
	v_pk_mul_f32 v[70:71], v[164:165], v[70:71] op_sel:[1,0]
	v_pk_fma_f32 v[72:73], v[140:141], v[72:73], v[144:145]
	v_pk_fma_f32 v[74:75], v[142:143], v[74:75], v[146:147]
	v_pk_fma_f32 v[68:69], v[132:133], v[68:69], v[136:137]
	v_pk_fma_f32 v[70:71], v[134:135], v[70:71], v[138:139]
	v_cvt_pk_f16_f32 v170, v72, v73
	v_cvt_pk_f16_f32 v171, v74, v75
	v_cvt_pk_f16_f32 v172, v68, v69
	v_cvt_pk_f16_f32 v173, v70, v71
	v_add_u32_e32 v170, 0x20002, v170
	v_add_u32_e32 v171, 0x20002, v171
	v_add_u32_e32 v172, 0x20002, v172
	v_add_u32_e32 v173, 0x20002, v173
	v_and_b32_e32 v170, 0xfffcfffc, v170
	v_and_b32_e32 v171, 0xfffcfffc, v171
	v_and_b32_e32 v172, 0xfffcfffc, v172
	v_and_b32_e32 v173, 0xfffcfffc, v173
	global_store_dwordx4 v[176:177], v[170:173], off offset:256
	ds_read_b64 v[164:165], v32 offset:9344
	v_add_co_u32_e32 v176, vcc, 0x40000, v166
	v_addc_co_u32_e32 v177, vcc, 0, v167, vcc
	s_waitcnt lgkmcnt(1)
	v_cndmask_b32_e64 v169, v229, v169, s[100:101]
	v_pk_add_f32 v[64:65], v[64:65], v[168:169] op_sel_hi:[1,0] neg_lo:[0,1] neg_hi:[0,1]
	v_pk_add_f32 v[66:67], v[66:67], v[168:169] op_sel_hi:[1,0] neg_lo:[0,1] neg_hi:[0,1]
	v_pk_add_f32 v[60:61], v[60:61], v[168:169] op_sel_hi:[1,0] neg_lo:[0,1] neg_hi:[0,1]
	v_pk_add_f32 v[62:63], v[62:63], v[168:169] op_sel_hi:[1,0] neg_lo:[0,1] neg_hi:[0,1]
	v_pk_mul_f32 v[64:65], v[168:169], v[64:65] op_sel:[1,0]
	v_pk_mul_f32 v[66:67], v[168:169], v[66:67] op_sel:[1,0]
	v_pk_mul_f32 v[60:61], v[168:169], v[60:61] op_sel:[1,0]
	v_pk_mul_f32 v[62:63], v[168:169], v[62:63] op_sel:[1,0]
	v_pk_fma_f32 v[64:65], v[160:161], v[64:65], v[156:157]
	v_pk_fma_f32 v[66:67], v[162:163], v[66:67], v[158:159]
	v_pk_fma_f32 v[60:61], v[148:149], v[60:61], v[152:153]
	v_pk_fma_f32 v[62:63], v[150:151], v[62:63], v[154:155]
	v_cvt_pk_f16_f32 v170, v64, v65
	v_cvt_pk_f16_f32 v171, v66, v67
	v_cvt_pk_f16_f32 v172, v60, v61
	v_cvt_pk_f16_f32 v173, v62, v63
	v_add_u32_e32 v170, 0x20002, v170
	v_add_u32_e32 v171, 0x20002, v171
	v_add_u32_e32 v172, 0x20002, v172
	v_add_u32_e32 v173, 0x20002, v173
	v_and_b32_e32 v170, 0xfffcfffc, v170
	v_and_b32_e32 v171, 0xfffcfffc, v171
	v_and_b32_e32 v172, 0xfffcfffc, v172
	v_and_b32_e32 v173, 0xfffcfffc, v173
	global_store_dwordx4 v[176:177], v[170:173], off
	v_pk_add_f32 v[56:57], v[56:57], v[168:169] op_sel_hi:[1,0] neg_lo:[0,1] neg_hi:[0,1]
	v_pk_add_f32 v[58:59], v[58:59], v[168:169] op_sel_hi:[1,0] neg_lo:[0,1] neg_hi:[0,1]
	v_pk_add_f32 v[52:53], v[52:53], v[168:169] op_sel_hi:[1,0] neg_lo:[0,1] neg_hi:[0,1]
	v_pk_add_f32 v[54:55], v[54:55], v[168:169] op_sel_hi:[1,0] neg_lo:[0,1] neg_hi:[0,1]
	v_pk_mul_f32 v[56:57], v[168:169], v[56:57] op_sel:[1,0]
	v_pk_mul_f32 v[58:59], v[168:169], v[58:59] op_sel:[1,0]
	v_pk_mul_f32 v[52:53], v[168:169], v[52:53] op_sel:[1,0]
	v_pk_mul_f32 v[54:55], v[168:169], v[54:55] op_sel:[1,0]
	v_pk_fma_f32 v[56:57], v[140:141], v[56:57], v[144:145]
	v_pk_fma_f32 v[58:59], v[142:143], v[58:59], v[146:147]
	v_pk_fma_f32 v[52:53], v[132:133], v[52:53], v[136:137]
	v_pk_fma_f32 v[54:55], v[134:135], v[54:55], v[138:139]
	v_cvt_pk_f16_f32 v170, v56, v57
	v_cvt_pk_f16_f32 v171, v58, v59
	v_cvt_pk_f16_f32 v172, v52, v53
	v_cvt_pk_f16_f32 v173, v54, v55
	v_add_u32_e32 v170, 0x20002, v170
	v_add_u32_e32 v171, 0x20002, v171
	v_add_u32_e32 v172, 0x20002, v172
	v_add_u32_e32 v173, 0x20002, v173
	v_and_b32_e32 v170, 0xfffcfffc, v170
	v_and_b32_e32 v171, 0xfffcfffc, v171
	v_and_b32_e32 v172, 0xfffcfffc, v172
	v_and_b32_e32 v173, 0xfffcfffc, v173
	global_store_dwordx4 v[176:177], v[170:173], off offset:256
	ds_read_b64 v[168:169], v32 offset:9472
	v_add_co_u32_e32 v176, vcc, 0x48000, v166
	v_addc_co_u32_e32 v177, vcc, 0, v167, vcc
	s_waitcnt lgkmcnt(1)
; template <unsigned D> __device__ __forceinline__ u32x4 rd8(u32x4 w) { w.x = rd<D>(w.x); w.y = rd<D>(w.y); w.z = rd<D>(w.z); w.w = rd<D>(w.w); return w; }
; __device__ __forceinline__ u32x4 pk8(const f32x4 v0, const f32x4 v1) { u32x4 w; w.x = pk_f16(v0[0], v0[1]); w.y = pk_f16(v0[2], v0[3]); w.z = pk_f16(v1[0], v1[1]); w.w = pk_f16(v1[2], v1[3]); return w; }
; __device__ __forceinline__ unsigned pk4_fp8(float a, float b, float c, float d) { int w = __builtin_amdgcn_cvt_pk_fp8_f32(a, b, 0, false); w = __builtin_amdgcn_cvt_pk_fp8_f32(c, d, w, true); return (unsigned)w; }
;     __device__ __forceinline__ void fused(f32x4 (&acc)[2][2][4][2], const GUnit& u, int wr, int wc, int fr, int fq, LAS unsigned char* lds, int wid, int lane) const {
;     ...
; #pragma unroll
;         for (int ai = 0; ai < 2; ++ai)
; #pragma unroll
;             for (int m = 0; m < 4; ++m) { const int r = ai * 128 + wr * 64 + m * 16 + fr; const f32x2 sr = S[r]; const size_t row = (size_t)(u.pm * 256 + r);
; #pragma unroll
;                 for (int bj = 0; bj < 2; ++bj) { const int col = gcol0 + bj * 128;
;                     f32x4 y0 = (acc[ai][bj][m][0] - sr.x) * sr.y * gv[bj][0] + bv[bj][0], y1 = (acc[ai][bj][m][1] - sr.x) * sr.y * gv[bj][1] + bv[bj][1];
;                     if (bad) { y0 = (f32x4){qnan, qnan, qnan, qnan}; y1 = y0; }
;                     if (last) { *(f32x4*)(out + row * 1024 + col) = y0; *(f32x4*)(out + row * 1024 + col + 4) = y1; }
;                     else { *(u32x4*)(H16 + row * 1024 + col) = rd8<D_H>(pk8(y0, y1));
;                            if (h8out) { u32x2 q8v; q8v.x = pk4_fp8(y0[0], y0[1], y0[2], y0[3]); q8v.y = pk4_fp8(y1[0], y1[1], y1[2], y1[3]); *(u32x2*)(ws + WS_H8 + row * 1024 + col) = q8v; } } }
	v_cndmask_b32_e64 v165, v229, v165, s[100:101]
	v_pk_add_f32 v[48:49], v[48:49], v[164:165] op_sel_hi:[1,0] neg_lo:[0,1] neg_hi:[0,1]
	v_pk_add_f32 v[50:51], v[50:51], v[164:165] op_sel_hi:[1,0] neg_lo:[0,1] neg_hi:[0,1]
	v_pk_add_f32 v[44:45], v[44:45], v[164:165] op_sel_hi:[1,0] neg_lo:[0,1] neg_hi:[0,1]
	v_pk_add_f32 v[46:47], v[46:47], v[164:165] op_sel_hi:[1,0] neg_lo:[0,1] neg_hi:[0,1]
	v_pk_mul_f32 v[48:49], v[164:165], v[48:49] op_sel:[1,0]
	v_pk_mul_f32 v[50:51], v[164:165], v[50:51] op_sel:[1,0]
	v_pk_mul_f32 v[44:45], v[164:165], v[44:45] op_sel:[1,0]
	v_pk_mul_f32 v[46:47], v[164:165], v[46:47] op_sel:[1,0]
	v_pk_fma_f32 v[48:49], v[160:161], v[48:49], v[156:157]
	v_pk_fma_f32 v[50:51], v[162:163], v[50:51], v[158:159]
	v_pk_fma_f32 v[44:45], v[148:149], v[44:45], v[152:153]
	v_pk_fma_f32 v[46:47], v[150:151], v[46:47], v[154:155]
	v_cvt_pk_f16_f32 v170, v48, v49
	v_cvt_pk_f16_f32 v171, v50, v51
	v_cvt_pk_f16_f32 v172, v44, v45
	v_cvt_pk_f16_f32 v173, v46, v47
	v_add_u32_e32 v170, 0x20002, v170
	v_add_u32_e32 v171, 0x20002, v171
	v_add_u32_e32 v172, 0x20002, v172
	v_add_u32_e32 v173, 0x20002, v173
	v_and_b32_e32 v170, 0xfffcfffc, v170
	v_and_b32_e32 v171, 0xfffcfffc, v171
	v_and_b32_e32 v172, 0xfffcfffc, v172
	v_and_b32_e32 v173, 0xfffcfffc, v173
	global_store_dwordx4 v[176:177], v[170:173], off
	v_pk_add_f32 v[40:41], v[40:41], v[164:165] op_sel_hi:[1,0] neg_lo:[0,1] neg_hi:[0,1]
	v_pk_add_f32 v[42:43], v[42:43], v[164:165] op_sel_hi:[1,0] neg_lo:[0,1] neg_hi:[0,1]
	v_pk_add_f32 v[36:37], v[36:37], v[164:165] op_sel_hi:[1,0] neg_lo:[0,1] neg_hi:[0,1]
	v_pk_add_f32 v[38:39], v[38:39], v[164:165] op_sel_hi:[1,0] neg_lo:[0,1] neg_hi:[0,1]
	v_pk_mul_f32 v[40:41], v[164:165], v[40:41] op_sel:[1,0]
	v_pk_mul_f32 v[42:43], v[164:165], v[42:43] op_sel:[1,0]
	v_pk_mul_f32 v[36:37], v[164:165], v[36:37] op_sel:[1,0]
	v_pk_mul_f32 v[38:39], v[164:165], v[38:39] op_sel:[1,0]
	v_pk_fma_f32 v[40:41], v[140:141], v[40:41], v[144:145]
	v_pk_fma_f32 v[42:43], v[142:143], v[42:43], v[146:147]
	v_pk_fma_f32 v[36:37], v[132:133], v[36:37], v[136:137]
	v_pk_fma_f32 v[38:39], v[134:135], v[38:39], v[138:139]
	v_cvt_pk_f16_f32 v170, v40, v41
	v_cvt_pk_f16_f32 v171, v42, v43
	v_cvt_pk_f16_f32 v172, v36, v37
	v_cvt_pk_f16_f32 v173, v38, v39
	v_add_u32_e32 v170, 0x20002, v170
	v_add_u32_e32 v171, 0x20002, v171
	v_add_u32_e32 v172, 0x20002, v172
	v_add_u32_e32 v173, 0x20002, v173
	v_and_b32_e32 v170, 0xfffcfffc, v170
	v_and_b32_e32 v171, 0xfffcfffc, v171
	v_and_b32_e32 v172, 0xfffcfffc, v172
	v_and_b32_e32 v173, 0xfffcfffc, v173
	global_store_dwordx4 v[176:177], v[170:173], off offset:256
	ds_read_b64 v[164:165], v32 offset:9600
	v_add_co_u32_e32 v176, vcc, 0x50000, v166
	v_addc_co_u32_e32 v177, vcc, 0, v167, vcc
	s_waitcnt lgkmcnt(1)
; template <unsigned D> __device__ __forceinline__ u32x4 rd8(u32x4 w) { w.x = rd<D>(w.x); w.y = rd<D>(w.y); w.z = rd<D>(w.z); w.w = rd<D>(w.w); return w; }
; __device__ __forceinline__ u32x4 pk8(const f32x4 v0, const f32x4 v1) { u32x4 w; w.x = pk_f16(v0[0], v0[1]); w.y = pk_f16(v0[2], v0[3]); w.z = pk_f16(v1[0], v1[1]); w.w = pk_f16(v1[2], v1[3]); return w; }
; __device__ __forceinline__ unsigned pk4_fp8(float a, float b, float c, float d) { int w = __builtin_amdgcn_cvt_pk_fp8_f32(a, b, 0, false); w = __builtin_amdgcn_cvt_pk_fp8_f32(c, d, w, true); return (unsigned)w; }
;     __device__ __forceinline__ void fused(f32x4 (&acc)[2][2][4][2], const GUnit& u, int wr, int wc, int fr, int fq, LAS unsigned char* lds, int wid, int lane) const {
;     ...
; #pragma unroll
;         for (int ai = 0; ai < 2; ++ai)
; #pragma unroll
;             for (int m = 0; m < 4; ++m) { const int r = ai * 128 + wr * 64 + m * 16 + fr; const f32x2 sr = S[r]; const size_t row = (size_t)(u.pm * 256 + r);
; #pragma unroll
;                 for (int bj = 0; bj < 2; ++bj) { const int col = gcol0 + bj * 128;
;                     f32x4 y0 = (acc[ai][bj][m][0] - sr.x) * sr.y * gv[bj][0] + bv[bj][0], y1 = (acc[ai][bj][m][1] - sr.x) * sr.y * gv[bj][1] + bv[bj][1];
;                     if (bad) { y0 = (f32x4){qnan, qnan, qnan, qnan}; y1 = y0; }
;                     if (last) { *(f32x4*)(out + row * 1024 + col) = y0; *(f32x4*)(out + row * 1024 + col + 4) = y1; }
;                     else { *(u32x4*)(H16 + row * 1024 + col) = rd8<D_H>(pk8(y0, y1));
;                            if (h8out) { u32x2 q8v; q8v.x = pk4_fp8(y0[0], y0[1], y0[2], y0[3]); q8v.y = pk4_fp8(y1[0], y1[1], y1[2], y1[3]); *(u32x2*)(ws + WS_H8 + row * 1024 + col) = q8v; } } }
	v_cndmask_b32_e64 v169, v229, v169, s[100:101]
	v_pk_add_f32 v[28:29], v[28:29], v[168:169] op_sel_hi:[1,0] neg_lo:[0,1] neg_hi:[0,1]
	v_pk_add_f32 v[30:31], v[30:31], v[168:169] op_sel_hi:[1,0] neg_lo:[0,1] neg_hi:[0,1]
	v_pk_add_f32 v[24:25], v[24:25], v[168:169] op_sel_hi:[1,0] neg_lo:[0,1] neg_hi:[0,1]
	v_pk_add_f32 v[26:27], v[26:27], v[168:169] op_sel_hi:[1,0] neg_lo:[0,1] neg_hi:[0,1]
	v_pk_mul_f32 v[28:29], v[168:169], v[28:29] op_sel:[1,0]
	v_pk_mul_f32 v[30:31], v[168:169], v[30:31] op_sel:[1,0]
	v_pk_mul_f32 v[24:25], v[168:169], v[24:25] op_sel:[1,0]
	v_pk_mul_f32 v[26:27], v[168:169], v[26:27] op_sel:[1,0]
	v_pk_fma_f32 v[28:29], v[160:161], v[28:29], v[156:157]
	v_pk_fma_f32 v[30:31], v[162:163], v[30:31], v[158:159]
	v_pk_fma_f32 v[24:25], v[148:149], v[24:25], v[152:153]
	v_pk_fma_f32 v[26:27], v[150:151], v[26:27], v[154:155]
	v_cvt_pk_f16_f32 v170, v28, v29
	v_cvt_pk_f16_f32 v171, v30, v31
	v_cvt_pk_f16_f32 v172, v24, v25
	v_cvt_pk_f16_f32 v173, v26, v27
	v_add_u32_e32 v170, 0x20002, v170
	v_add_u32_e32 v171, 0x20002, v171
	v_add_u32_e32 v172, 0x20002, v172
	v_add_u32_e32 v173, 0x20002, v173
	v_and_b32_e32 v170, 0xfffcfffc, v170
	v_and_b32_e32 v171, 0xfffcfffc, v171
	v_and_b32_e32 v172, 0xfffcfffc, v172
	v_and_b32_e32 v173, 0xfffcfffc, v173
	global_store_dwordx4 v[176:177], v[170:173], off
	v_pk_add_f32 v[20:21], v[20:21], v[168:169] op_sel_hi:[1,0] neg_lo:[0,1] neg_hi:[0,1]
	v_pk_add_f32 v[22:23], v[22:23], v[168:169] op_sel_hi:[1,0] neg_lo:[0,1] neg_hi:[0,1]
	v_pk_add_f32 v[16:17], v[16:17], v[168:169] op_sel_hi:[1,0] neg_lo:[0,1] neg_hi:[0,1]
	v_pk_add_f32 v[18:19], v[18:19], v[168:169] op_sel_hi:[1,0] neg_lo:[0,1] neg_hi:[0,1]
	v_pk_mul_f32 v[20:21], v[168:169], v[20:21] op_sel:[1,0]
	v_pk_mul_f32 v[22:23], v[168:169], v[22:23] op_sel:[1,0]
	v_pk_mul_f32 v[16:17], v[168:169], v[16:17] op_sel:[1,0]
	v_pk_mul_f32 v[18:19], v[168:169], v[18:19] op_sel:[1,0]
	v_pk_fma_f32 v[20:21], v[140:141], v[20:21], v[144:145]
	v_pk_fma_f32 v[22:23], v[142:143], v[22:23], v[146:147]
	v_pk_fma_f32 v[16:17], v[132:133], v[16:17], v[136:137]
	v_pk_fma_f32 v[18:19], v[134:135], v[18:19], v[138:139]
	v_cvt_pk_f16_f32 v170, v20, v21
	v_cvt_pk_f16_f32 v171, v22, v23
	v_cvt_pk_f16_f32 v172, v16, v17
	v_cvt_pk_f16_f32 v173, v18, v19
	v_add_u32_e32 v170, 0x20002, v170
	v_add_u32_e32 v171, 0x20002, v171
	v_add_u32_e32 v172, 0x20002, v172
	v_add_u32_e32 v173, 0x20002, v173
	v_and_b32_e32 v170, 0xfffcfffc, v170
	v_and_b32_e32 v171, 0xfffcfffc, v171
	v_and_b32_e32 v172, 0xfffcfffc, v172
	v_and_b32_e32 v173, 0xfffcfffc, v173
	global_store_dwordx4 v[176:177], v[170:173], off offset:256
	v_add_co_u32_e32 v176, vcc, 0x58000, v166
	v_addc_co_u32_e32 v177, vcc, 0, v167, vcc
	s_waitcnt lgkmcnt(0)
	v_cndmask_b32_e64 v165, v229, v165, s[100:101]
	v_pk_add_f32 v[12:13], v[12:13], v[164:165] op_sel_hi:[1,0] neg_lo:[0,1] neg_hi:[0,1]
	v_pk_add_f32 v[14:15], v[14:15], v[164:165] op_sel_hi:[1,0] neg_lo:[0,1] neg_hi:[0,1]
	v_pk_add_f32 v[8:9], v[8:9], v[164:165] op_sel_hi:[1,0] neg_lo:[0,1] neg_hi:[0,1]
	v_pk_add_f32 v[10:11], v[10:11], v[164:165] op_sel_hi:[1,0] neg_lo:[0,1] neg_hi:[0,1]
	v_pk_mul_f32 v[12:13], v[164:165], v[12:13] op_sel:[1,0]
	v_pk_mul_f32 v[14:15], v[164:165], v[14:15] op_sel:[1,0]
	v_pk_mul_f32 v[8:9], v[164:165], v[8:9] op_sel:[1,0]
	v_pk_mul_f32 v[10:11], v[164:165], v[10:11] op_sel:[1,0]
	v_pk_fma_f32 v[12:13], v[160:161], v[12:13], v[156:157]
	v_pk_fma_f32 v[14:15], v[162:163], v[14:15], v[158:159]
	v_pk_fma_f32 v[8:9], v[148:149], v[8:9], v[152:153]
	v_pk_fma_f32 v[10:11], v[150:151], v[10:11], v[154:155]
	v_cvt_pk_f16_f32 v170, v12, v13
	v_cvt_pk_f16_f32 v171, v14, v15
	v_cvt_pk_f16_f32 v172, v8, v9
	v_cvt_pk_f16_f32 v173, v10, v11
	v_add_u32_e32 v170, 0x20002, v170
	v_add_u32_e32 v171, 0x20002, v171
	v_add_u32_e32 v172, 0x20002, v172
	v_add_u32_e32 v173, 0x20002, v173
	v_and_b32_e32 v170, 0xfffcfffc, v170
	v_and_b32_e32 v171, 0xfffcfffc, v171
	v_and_b32_e32 v172, 0xfffcfffc, v172
	v_and_b32_e32 v173, 0xfffcfffc, v173
	global_store_dwordx4 v[176:177], v[170:173], off
	v_pk_add_f32 v[4:5], v[4:5], v[164:165] op_sel_hi:[1,0] neg_lo:[0,1] neg_hi:[0,1]
	v_pk_add_f32 v[6:7], v[6:7], v[164:165] op_sel_hi:[1,0] neg_lo:[0,1] neg_hi:[0,1]
	v_pk_add_f32 v[0:1], v[0:1], v[164:165] op_sel_hi:[1,0] neg_lo:[0,1] neg_hi:[0,1]
	v_pk_add_f32 v[2:3], v[2:3], v[164:165] op_sel_hi:[1,0] neg_lo:[0,1] neg_hi:[0,1]
	v_pk_mul_f32 v[4:5], v[164:165], v[4:5] op_sel:[1,0]
	v_pk_mul_f32 v[6:7], v[164:165], v[6:7] op_sel:[1,0]
	v_pk_mul_f32 v[0:1], v[164:165], v[0:1] op_sel:[1,0]
	v_pk_mul_f32 v[2:3], v[164:165], v[2:3] op_sel:[1,0]
	v_pk_fma_f32 v[4:5], v[140:141], v[4:5], v[144:145]
	v_pk_fma_f32 v[6:7], v[142:143], v[6:7], v[146:147]
	v_pk_fma_f32 v[0:1], v[132:133], v[0:1], v[136:137]
	v_pk_fma_f32 v[2:3], v[134:135], v[2:3], v[138:139]
	v_cvt_pk_f16_f32 v170, v4, v5
	v_cvt_pk_f16_f32 v171, v6, v7
	v_cvt_pk_f16_f32 v172, v0, v1
	v_cvt_pk_f16_f32 v173, v2, v3
	v_add_u32_e32 v170, 0x20002, v170
	v_add_u32_e32 v171, 0x20002, v171
	v_add_u32_e32 v172, 0x20002, v172
	v_add_u32_e32 v173, 0x20002, v173
	v_and_b32_e32 v170, 0xfffcfffc, v170
	v_and_b32_e32 v171, 0xfffcfffc, v171
	v_and_b32_e32 v172, 0xfffcfffc, v172
	v_and_b32_e32 v173, 0xfffcfffc, v173
	global_store_dwordx4 v[176:177], v[170:173], off offset:256
	v_mov_b32_e32 v233, v226
	s_branch .LBB0_567
